# nt cache hint on the once-read f32 weight / ada_w streaming loads of the weight-conversion code, on top of barrier edits
# speedup vs baseline: 1.0087x; 1.0033x over previous
.LBB0_34:
	s_mov_b32 s14, 0xfff4c000
	v_add_co_u32_e32 v26, vcc, s14, v56
	s_mov_b32 s14, 0xfff58000
	s_nop 0
	v_addc_co_u32_e32 v27, vcc, -1, v57, vcc
	v_add_co_u32_e32 v62, vcc, s14, v56
	v_mov_b32_e32 v77, s16
	s_nop 0
	v_addc_co_u32_e32 v63, vcc, -1, v57, vcc
	global_load_dwordx4 v[58:61], v[26:27], off nt
	s_nop 0
	global_load_dwordx4 v[62:65], v[62:63], off nt
	ds_read_b128 v[66:69], v77
	ds_read_b128 v[70:73], v77 offset:16
	s_mov_b32 s14, 0xfff64000
	s_add_i32 s17, s17, 16
	s_addk_i32 s16, 0x300
	s_cmp_ge_i32 s17, s23
	s_waitcnt vmcnt(1) lgkmcnt(1)
	v_pk_fma_f32 v[74:75], v[58:59], v[66:67], v[6:7] op_sel_hi:[1,0,1]
	v_mov_b32_e32 v6, v69
	v_pk_fma_f32 v[26:27], v[60:61], v[66:67], v[8:9] op_sel_hi:[1,0,1]
	v_pk_fma_f32 v[16:17], v[60:61], v[68:69], v[16:17] op_sel_hi:[1,0,1]
	v_pk_fma_f32 v[14:15], v[58:59], v[68:69], v[14:15] op_sel_hi:[1,0,1]
	v_pk_fma_f32 v[30:31], v[60:61], v[6:7], v[30:31] op_sel_hi:[1,0,1]
	v_pk_fma_f32 v[68:69], v[58:59], v[6:7], v[28:29] op_sel_hi:[1,0,1]
	ds_read_b128 v[6:9], v77 offset:32
	v_pk_fma_f32 v[78:79], v[60:61], v[66:67], v[12:13] op_sel:[0,1,0]
	v_pk_fma_f32 v[66:67], v[58:59], v[66:67], v[10:11] op_sel:[0,1,0]
	s_waitcnt lgkmcnt(1)
	v_mov_b32_e32 v10, v73
	v_pk_fma_f32 v[28:29], v[60:61], v[70:71], v[34:35] op_sel_hi:[1,0,1]
	v_pk_fma_f32 v[34:35], v[60:61], v[70:71], v[38:39] op_sel:[0,1,0]
	v_pk_fma_f32 v[38:39], v[60:61], v[10:11], v[42:43] op_sel_hi:[1,0,1]
	v_pk_fma_f32 v[40:41], v[58:59], v[10:11], v[40:41] op_sel_hi:[1,0,1]
	ds_read_b128 v[10:13], v77 offset:48
	s_waitcnt lgkmcnt(1)
	v_pk_fma_f32 v[42:43], v[60:61], v[6:7], v[46:47] op_sel_hi:[1,0,1]
	v_pk_fma_f32 v[44:45], v[58:59], v[6:7], v[44:45] op_sel_hi:[1,0,1]
	v_pk_fma_f32 v[46:47], v[60:61], v[6:7], v[50:51] op_sel:[0,1,0]
	v_pk_fma_f32 v[48:49], v[58:59], v[6:7], v[48:49] op_sel:[0,1,0]
	v_mov_b32_e32 v6, v9
	v_pk_fma_f32 v[32:33], v[58:59], v[70:71], v[32:33] op_sel_hi:[1,0,1]
	v_pk_fma_f32 v[36:37], v[58:59], v[70:71], v[36:37] op_sel:[0,1,0]
	v_pk_fma_f32 v[18:19], v[58:59], v[72:73], v[18:19] op_sel_hi:[1,0,1]
	v_pk_fma_f32 v[22:23], v[58:59], v[8:9], v[22:23] op_sel_hi:[1,0,1]
	v_pk_fma_f32 v[50:51], v[60:61], v[6:7], v[4:5] op_sel_hi:[1,0,1]
	v_pk_fma_f32 v[58:59], v[58:59], v[6:7], v[2:3] op_sel_hi:[1,0,1]
	ds_read_b128 v[2:5], v77 offset:64
	v_pk_fma_f32 v[20:21], v[60:61], v[72:73], v[20:21] op_sel_hi:[1,0,1]
	v_pk_fma_f32 v[24:25], v[60:61], v[8:9], v[24:25] op_sel_hi:[1,0,1]
	v_add_co_u32_e32 v60, vcc, s14, v56
	s_waitcnt vmcnt(0) lgkmcnt(1)
	v_pk_fma_f32 v[72:73], v[64:65], v[10:11], v[26:27] op_sel_hi:[1,0,1]
	v_addc_co_u32_e32 v61, vcc, -1, v57, vcc
	ds_read_b128 v[6:9], v77 offset:80
	s_waitcnt lgkmcnt(1)
	v_pk_fma_f32 v[80:81], v[64:65], v[2:3], v[28:29] op_sel_hi:[1,0,1]
	global_load_dwordx4 v[26:29], v[60:61], off nt
	s_mov_b32 s14, 0xfff70000
	v_pk_fma_f32 v[20:21], v[64:65], v[4:5], v[20:21] op_sel_hi:[1,0,1]
	v_pk_fma_f32 v[18:19], v[62:63], v[4:5], v[18:19] op_sel_hi:[1,0,1]
	v_add_co_u32_e32 v4, vcc, s14, v56
	v_pk_fma_f32 v[32:33], v[62:63], v[2:3], v[32:33] op_sel_hi:[1,0,1]
	v_pk_fma_f32 v[34:35], v[64:65], v[2:3], v[34:35] op_sel:[0,1,0]
	v_pk_fma_f32 v[36:37], v[62:63], v[2:3], v[36:37] op_sel:[0,1,0]
	v_mov_b32_e32 v2, v5
	v_addc_co_u32_e32 v5, vcc, -1, v57, vcc
	v_pk_fma_f32 v[74:75], v[62:63], v[10:11], v[74:75] op_sel_hi:[1,0,1]
	v_pk_fma_f32 v[78:79], v[64:65], v[10:11], v[78:79] op_sel:[0,1,0]
	v_pk_fma_f32 v[66:67], v[62:63], v[10:11], v[66:67] op_sel:[0,1,0]
	s_waitcnt lgkmcnt(0)
	v_pk_fma_f32 v[42:43], v[64:65], v[6:7], v[42:43] op_sel_hi:[1,0,1]
	v_pk_fma_f32 v[44:45], v[62:63], v[6:7], v[44:45] op_sel_hi:[1,0,1]
	v_pk_fma_f32 v[46:47], v[64:65], v[6:7], v[46:47] op_sel:[0,1,0]
	v_pk_fma_f32 v[48:49], v[62:63], v[6:7], v[48:49] op_sel:[0,1,0]
	v_pk_fma_f32 v[24:25], v[64:65], v[8:9], v[24:25] op_sel_hi:[1,0,1]
	v_pk_fma_f32 v[82:83], v[62:63], v[8:9], v[22:23] op_sel_hi:[1,0,1]
	v_mov_b32_e32 v10, v9
	global_load_dwordx4 v[6:9], v[4:5], off nt
	v_mov_b32_e32 v70, v13
	v_pk_fma_f32 v[16:17], v[64:65], v[12:13], v[16:17] op_sel_hi:[1,0,1]
	v_pk_fma_f32 v[14:15], v[62:63], v[12:13], v[14:15] op_sel_hi:[1,0,1]
	v_pk_fma_f32 v[38:39], v[64:65], v[2:3], v[38:39] op_sel_hi:[1,0,1]
	v_pk_fma_f32 v[40:41], v[62:63], v[2:3], v[40:41] op_sel_hi:[1,0,1]
	v_pk_fma_f32 v[50:51], v[64:65], v[10:11], v[50:51] op_sel_hi:[1,0,1]
	v_pk_fma_f32 v[58:59], v[62:63], v[10:11], v[58:59] op_sel_hi:[1,0,1]
	ds_read_b128 v[2:5], v77 offset:96
	ds_read_b128 v[10:13], v77 offset:112
	v_pk_fma_f32 v[60:61], v[64:65], v[70:71], v[30:31] op_sel_hi:[1,0,1]
	v_pk_fma_f32 v[68:69], v[62:63], v[70:71], v[68:69] op_sel_hi:[1,0,1]
	s_mov_b32 s14, 0xfff7c000
	s_waitcnt lgkmcnt(0)
	v_mov_b32_e32 v84, v13
	s_waitcnt vmcnt(1)
	v_pk_fma_f32 v[62:63], v[28:29], v[2:3], v[72:73] op_sel_hi:[1,0,1]
	v_pk_fma_f32 v[64:65], v[26:27], v[2:3], v[74:75] op_sel_hi:[1,0,1]
	v_pk_fma_f32 v[70:71], v[28:29], v[2:3], v[78:79] op_sel:[0,1,0]
	v_pk_fma_f32 v[66:67], v[26:27], v[2:3], v[66:67] op_sel:[0,1,0]
	v_pk_fma_f32 v[72:73], v[28:29], v[4:5], v[16:17] op_sel_hi:[1,0,1]
	v_pk_fma_f32 v[74:75], v[26:27], v[4:5], v[14:15] op_sel_hi:[1,0,1]
	v_mov_b32_e32 v78, v5
	v_pk_fma_f32 v[86:87], v[26:27], v[10:11], v[32:33] op_sel_hi:[1,0,1]
	ds_read_b128 v[2:5], v77 offset:128
	ds_read_b128 v[30:33], v77 offset:144
	v_pk_fma_f32 v[80:81], v[28:29], v[10:11], v[80:81] op_sel_hi:[1,0,1]
	v_pk_fma_f32 v[34:35], v[28:29], v[10:11], v[34:35] op_sel:[0,1,0]
	v_pk_fma_f32 v[36:37], v[26:27], v[10:11], v[36:37] op_sel:[0,1,0]
	s_waitcnt lgkmcnt(1)
	v_pk_fma_f32 v[14:15], v[28:29], v[2:3], v[42:43] op_sel_hi:[1,0,1]
	v_mov_b32_e32 v42, v5
	v_pk_fma_f32 v[88:89], v[28:29], v[12:13], v[20:21] op_sel_hi:[1,0,1]
	v_pk_fma_f32 v[90:91], v[26:27], v[12:13], v[18:19] op_sel_hi:[1,0,1]
	v_pk_fma_f32 v[16:17], v[26:27], v[2:3], v[44:45] op_sel_hi:[1,0,1]
	v_pk_fma_f32 v[18:19], v[28:29], v[2:3], v[46:47] op_sel:[0,1,0]
	v_pk_fma_f32 v[20:21], v[26:27], v[2:3], v[48:49] op_sel:[0,1,0]
	v_pk_fma_f32 v[22:23], v[28:29], v[4:5], v[24:25] op_sel_hi:[1,0,1]
	v_pk_fma_f32 v[24:25], v[26:27], v[4:5], v[82:83] op_sel_hi:[1,0,1]
	v_pk_fma_f32 v[2:3], v[28:29], v[78:79], v[60:61] op_sel_hi:[1,0,1]
	v_pk_fma_f32 v[4:5], v[26:27], v[78:79], v[68:69] op_sel_hi:[1,0,1]
	v_pk_fma_f32 v[10:11], v[28:29], v[84:85], v[38:39] op_sel_hi:[1,0,1]
	v_pk_fma_f32 v[12:13], v[26:27], v[84:85], v[40:41] op_sel_hi:[1,0,1]
	v_pk_fma_f32 v[40:41], v[28:29], v[42:43], v[50:51] op_sel_hi:[1,0,1]
	v_pk_fma_f32 v[42:43], v[26:27], v[42:43], v[58:59] op_sel_hi:[1,0,1]
	ds_read_b128 v[26:29], v77 offset:160
	v_add_co_u32_e32 v38, vcc, s14, v56
	s_waitcnt lgkmcnt(1)
	v_mov_b32_e32 v44, v33
	v_addc_co_u32_e32 v39, vcc, -1, v57, vcc
	s_waitcnt vmcnt(0)
	v_pk_fma_f32 v[46:47], v[8:9], v[30:31], v[62:63] op_sel_hi:[1,0,1]
	v_pk_fma_f32 v[48:49], v[6:7], v[30:31], v[64:65] op_sel_hi:[1,0,1]
	v_pk_fma_f32 v[50:51], v[8:9], v[30:31], v[70:71] op_sel:[0,1,0]
	v_pk_fma_f32 v[58:59], v[6:7], v[30:31], v[66:67] op_sel:[0,1,0]
	v_pk_fma_f32 v[60:61], v[8:9], v[32:33], v[72:73] op_sel_hi:[1,0,1]
	v_pk_fma_f32 v[62:63], v[6:7], v[32:33], v[74:75] op_sel_hi:[1,0,1]
	ds_read_b128 v[30:33], v77 offset:176
	s_waitcnt lgkmcnt(1)
	v_pk_fma_f32 v[64:65], v[8:9], v[26:27], v[80:81] op_sel_hi:[1,0,1]
	v_pk_fma_f32 v[66:67], v[6:7], v[26:27], v[86:87] op_sel_hi:[1,0,1]
	v_pk_fma_f32 v[34:35], v[8:9], v[26:27], v[34:35] op_sel:[0,1,0]
	v_pk_fma_f32 v[36:37], v[6:7], v[26:27], v[36:37] op_sel:[0,1,0]
	v_pk_fma_f32 v[68:69], v[8:9], v[28:29], v[88:89] op_sel_hi:[1,0,1]
	v_pk_fma_f32 v[70:71], v[6:7], v[28:29], v[90:91] op_sel_hi:[1,0,1]
	v_mov_b32_e32 v72, v29
	global_load_dwordx4 v[26:29], v[38:39], off nt
	s_mov_b32 s14, 0xfff88000
	v_add_co_u32_e32 v74, vcc, s14, v56
	v_pk_fma_f32 v[38:39], v[8:9], v[44:45], v[2:3] op_sel_hi:[1,0,1]
	s_nop 0
	v_addc_co_u32_e32 v75, vcc, -1, v57, vcc
	v_pk_fma_f32 v[44:45], v[6:7], v[44:45], v[4:5] op_sel_hi:[1,0,1]
	global_load_dwordx4 v[2:5], v[74:75], off nt
	s_waitcnt lgkmcnt(0)
	v_pk_fma_f32 v[14:15], v[8:9], v[30:31], v[14:15] op_sel_hi:[1,0,1]
	v_pk_fma_f32 v[16:17], v[6:7], v[30:31], v[16:17] op_sel_hi:[1,0,1]
	v_pk_fma_f32 v[18:19], v[8:9], v[30:31], v[18:19] op_sel:[0,1,0]
	v_pk_fma_f32 v[20:21], v[6:7], v[30:31], v[20:21] op_sel:[0,1,0]
	v_mov_b32_e32 v30, v33
	v_pk_fma_f32 v[22:23], v[8:9], v[32:33], v[22:23] op_sel_hi:[1,0,1]
	v_pk_fma_f32 v[24:25], v[6:7], v[32:33], v[24:25] op_sel_hi:[1,0,1]
	v_pk_fma_f32 v[74:75], v[8:9], v[72:73], v[10:11] op_sel_hi:[1,0,1]
	v_pk_fma_f32 v[72:73], v[6:7], v[72:73], v[12:13] op_sel_hi:[1,0,1]
	v_pk_fma_f32 v[40:41], v[8:9], v[30:31], v[40:41] op_sel_hi:[1,0,1]
	v_pk_fma_f32 v[42:43], v[6:7], v[30:31], v[42:43] op_sel_hi:[1,0,1]
	ds_read_b128 v[6:9], v77 offset:192
	ds_read_b128 v[10:13], v77 offset:208
	s_mov_b32 s14, 0xfff94000
	s_waitcnt lgkmcnt(1)
	v_mov_b32_e32 v78, v9
	s_waitcnt lgkmcnt(0)
	v_mov_b32_e32 v80, v13
	s_waitcnt vmcnt(1)
	v_pk_fma_f32 v[46:47], v[28:29], v[6:7], v[46:47] op_sel_hi:[1,0,1]
	v_pk_fma_f32 v[48:49], v[26:27], v[6:7], v[48:49] op_sel_hi:[1,0,1]
	v_pk_fma_f32 v[50:51], v[28:29], v[6:7], v[50:51] op_sel:[0,1,0]
	v_pk_fma_f32 v[58:59], v[26:27], v[6:7], v[58:59] op_sel:[0,1,0]
	v_pk_fma_f32 v[60:61], v[28:29], v[8:9], v[60:61] op_sel_hi:[1,0,1]
	v_pk_fma_f32 v[62:63], v[26:27], v[8:9], v[62:63] op_sel_hi:[1,0,1]
	ds_read_b128 v[6:9], v77 offset:224
	ds_read_b128 v[30:33], v77 offset:240
	v_pk_fma_f32 v[64:65], v[28:29], v[10:11], v[64:65] op_sel_hi:[1,0,1]
	v_pk_fma_f32 v[66:67], v[26:27], v[10:11], v[66:67] op_sel_hi:[1,0,1]
	v_pk_fma_f32 v[34:35], v[28:29], v[10:11], v[34:35] op_sel:[0,1,0]
	s_waitcnt lgkmcnt(1)
	v_mov_b32_e32 v82, v9
	v_pk_fma_f32 v[36:37], v[26:27], v[10:11], v[36:37] op_sel:[0,1,0]
	v_pk_fma_f32 v[68:69], v[28:29], v[12:13], v[68:69] op_sel_hi:[1,0,1]
	v_pk_fma_f32 v[70:71], v[26:27], v[12:13], v[70:71] op_sel_hi:[1,0,1]
	v_pk_fma_f32 v[14:15], v[28:29], v[6:7], v[14:15] op_sel_hi:[1,0,1]
	v_pk_fma_f32 v[16:17], v[26:27], v[6:7], v[16:17] op_sel_hi:[1,0,1]
	v_pk_fma_f32 v[18:19], v[28:29], v[6:7], v[18:19] op_sel:[0,1,0]
	v_pk_fma_f32 v[20:21], v[26:27], v[6:7], v[20:21] op_sel:[0,1,0]
	v_pk_fma_f32 v[22:23], v[28:29], v[8:9], v[22:23] op_sel_hi:[1,0,1]
	v_pk_fma_f32 v[24:25], v[26:27], v[8:9], v[24:25] op_sel_hi:[1,0,1]
	v_pk_fma_f32 v[6:7], v[28:29], v[78:79], v[38:39] op_sel_hi:[1,0,1]
	v_pk_fma_f32 v[8:9], v[26:27], v[78:79], v[44:45] op_sel_hi:[1,0,1]
	v_pk_fma_f32 v[10:11], v[28:29], v[80:81], v[74:75] op_sel_hi:[1,0,1]
	v_pk_fma_f32 v[12:13], v[26:27], v[80:81], v[72:73] op_sel_hi:[1,0,1]
	v_pk_fma_f32 v[40:41], v[28:29], v[82:83], v[40:41] op_sel_hi:[1,0,1]
	v_pk_fma_f32 v[42:43], v[26:27], v[82:83], v[42:43] op_sel_hi:[1,0,1]
	ds_read_b128 v[26:29], v77 offset:256
	v_add_co_u32_e32 v38, vcc, s14, v56
	s_waitcnt lgkmcnt(1)
	v_mov_b32_e32 v44, v33
	v_addc_co_u32_e32 v39, vcc, -1, v57, vcc
	s_waitcnt vmcnt(0)
	v_pk_fma_f32 v[46:47], v[4:5], v[30:31], v[46:47] op_sel_hi:[1,0,1]
	v_pk_fma_f32 v[48:49], v[2:3], v[30:31], v[48:49] op_sel_hi:[1,0,1]
	v_pk_fma_f32 v[50:51], v[4:5], v[30:31], v[50:51] op_sel:[0,1,0]
	v_pk_fma_f32 v[58:59], v[2:3], v[30:31], v[58:59] op_sel:[0,1,0]
	v_pk_fma_f32 v[60:61], v[4:5], v[32:33], v[60:61] op_sel_hi:[1,0,1]
	v_pk_fma_f32 v[62:63], v[2:3], v[32:33], v[62:63] op_sel_hi:[1,0,1]
	ds_read_b128 v[30:33], v77 offset:272
	s_waitcnt lgkmcnt(1)
	v_pk_fma_f32 v[64:65], v[4:5], v[26:27], v[64:65] op_sel_hi:[1,0,1]
	v_pk_fma_f32 v[66:67], v[2:3], v[26:27], v[66:67] op_sel_hi:[1,0,1]
	v_pk_fma_f32 v[34:35], v[4:5], v[26:27], v[34:35] op_sel:[0,1,0]
	v_pk_fma_f32 v[36:37], v[2:3], v[26:27], v[36:37] op_sel:[0,1,0]
	v_pk_fma_f32 v[68:69], v[4:5], v[28:29], v[68:69] op_sel_hi:[1,0,1]
	v_pk_fma_f32 v[70:71], v[2:3], v[28:29], v[70:71] op_sel_hi:[1,0,1]
	v_mov_b32_e32 v72, v29
	global_load_dwordx4 v[26:29], v[38:39], off nt
	s_mov_b32 s14, 0xfffa0000
	v_add_co_u32_e32 v74, vcc, s14, v56
	v_pk_fma_f32 v[38:39], v[4:5], v[44:45], v[6:7] op_sel_hi:[1,0,1]
	s_nop 0
	v_addc_co_u32_e32 v75, vcc, -1, v57, vcc
	v_pk_fma_f32 v[44:45], v[2:3], v[44:45], v[8:9] op_sel_hi:[1,0,1]
	global_load_dwordx4 v[6:9], v[74:75], off nt
	s_waitcnt lgkmcnt(0)
	v_pk_fma_f32 v[14:15], v[4:5], v[30:31], v[14:15] op_sel_hi:[1,0,1]
	v_pk_fma_f32 v[16:17], v[2:3], v[30:31], v[16:17] op_sel_hi:[1,0,1]
	v_pk_fma_f32 v[18:19], v[4:5], v[30:31], v[18:19] op_sel:[0,1,0]
	v_pk_fma_f32 v[20:21], v[2:3], v[30:31], v[20:21] op_sel:[0,1,0]
	v_mov_b32_e32 v30, v33
	v_pk_fma_f32 v[22:23], v[4:5], v[32:33], v[22:23] op_sel_hi:[1,0,1]
	v_pk_fma_f32 v[24:25], v[2:3], v[32:33], v[24:25] op_sel_hi:[1,0,1]
	v_pk_fma_f32 v[74:75], v[4:5], v[72:73], v[10:11] op_sel_hi:[1,0,1]
	v_pk_fma_f32 v[72:73], v[2:3], v[72:73], v[12:13] op_sel_hi:[1,0,1]
	v_pk_fma_f32 v[40:41], v[4:5], v[30:31], v[40:41] op_sel_hi:[1,0,1]
	v_pk_fma_f32 v[42:43], v[2:3], v[30:31], v[42:43] op_sel_hi:[1,0,1]
	ds_read_b128 v[2:5], v77 offset:288
	ds_read_b128 v[10:13], v77 offset:304
	s_mov_b32 s14, 0xfffac000
	s_waitcnt lgkmcnt(1)
	v_mov_b32_e32 v78, v5
	s_waitcnt lgkmcnt(0)
	v_mov_b32_e32 v80, v13
	s_waitcnt vmcnt(1)
	v_pk_fma_f32 v[46:47], v[28:29], v[2:3], v[46:47] op_sel_hi:[1,0,1]
	v_pk_fma_f32 v[48:49], v[26:27], v[2:3], v[48:49] op_sel_hi:[1,0,1]
	v_pk_fma_f32 v[50:51], v[28:29], v[2:3], v[50:51] op_sel:[0,1,0]
	v_pk_fma_f32 v[58:59], v[26:27], v[2:3], v[58:59] op_sel:[0,1,0]
	v_pk_fma_f32 v[60:61], v[28:29], v[4:5], v[60:61] op_sel_hi:[1,0,1]
	v_pk_fma_f32 v[62:63], v[26:27], v[4:5], v[62:63] op_sel_hi:[1,0,1]
	ds_read_b128 v[2:5], v77 offset:320
	ds_read_b128 v[30:33], v77 offset:336
	v_pk_fma_f32 v[64:65], v[28:29], v[10:11], v[64:65] op_sel_hi:[1,0,1]
	v_pk_fma_f32 v[66:67], v[26:27], v[10:11], v[66:67] op_sel_hi:[1,0,1]
	v_pk_fma_f32 v[34:35], v[28:29], v[10:11], v[34:35] op_sel:[0,1,0]
	s_waitcnt lgkmcnt(1)
	v_mov_b32_e32 v82, v5
	v_pk_fma_f32 v[36:37], v[26:27], v[10:11], v[36:37] op_sel:[0,1,0]
	v_pk_fma_f32 v[68:69], v[28:29], v[12:13], v[68:69] op_sel_hi:[1,0,1]
	v_pk_fma_f32 v[70:71], v[26:27], v[12:13], v[70:71] op_sel_hi:[1,0,1]
	v_pk_fma_f32 v[14:15], v[28:29], v[2:3], v[14:15] op_sel_hi:[1,0,1]
	v_pk_fma_f32 v[16:17], v[26:27], v[2:3], v[16:17] op_sel_hi:[1,0,1]
	v_pk_fma_f32 v[18:19], v[28:29], v[2:3], v[18:19] op_sel:[0,1,0]
	v_pk_fma_f32 v[20:21], v[26:27], v[2:3], v[20:21] op_sel:[0,1,0]
	v_pk_fma_f32 v[22:23], v[28:29], v[4:5], v[22:23] op_sel_hi:[1,0,1]
	v_pk_fma_f32 v[24:25], v[26:27], v[4:5], v[24:25] op_sel_hi:[1,0,1]
	v_pk_fma_f32 v[2:3], v[28:29], v[78:79], v[38:39] op_sel_hi:[1,0,1]
	v_pk_fma_f32 v[4:5], v[26:27], v[78:79], v[44:45] op_sel_hi:[1,0,1]
	v_pk_fma_f32 v[10:11], v[28:29], v[80:81], v[74:75] op_sel_hi:[1,0,1]
	v_pk_fma_f32 v[12:13], v[26:27], v[80:81], v[72:73] op_sel_hi:[1,0,1]
	v_pk_fma_f32 v[40:41], v[28:29], v[82:83], v[40:41] op_sel_hi:[1,0,1]
	v_pk_fma_f32 v[42:43], v[26:27], v[82:83], v[42:43] op_sel_hi:[1,0,1]
	ds_read_b128 v[26:29], v77 offset:352
	v_add_co_u32_e32 v38, vcc, s14, v56
	s_waitcnt lgkmcnt(1)
	v_mov_b32_e32 v44, v33
	v_addc_co_u32_e32 v39, vcc, -1, v57, vcc
	s_waitcnt vmcnt(0)
	v_pk_fma_f32 v[46:47], v[8:9], v[30:31], v[46:47] op_sel_hi:[1,0,1]
	v_pk_fma_f32 v[48:49], v[6:7], v[30:31], v[48:49] op_sel_hi:[1,0,1]
	v_pk_fma_f32 v[50:51], v[8:9], v[30:31], v[50:51] op_sel:[0,1,0]
	v_pk_fma_f32 v[58:59], v[6:7], v[30:31], v[58:59] op_sel:[0,1,0]
	v_pk_fma_f32 v[60:61], v[8:9], v[32:33], v[60:61] op_sel_hi:[1,0,1]
	v_pk_fma_f32 v[62:63], v[6:7], v[32:33], v[62:63] op_sel_hi:[1,0,1]
	ds_read_b128 v[30:33], v77 offset:368
	s_waitcnt lgkmcnt(1)
	v_pk_fma_f32 v[64:65], v[8:9], v[26:27], v[64:65] op_sel_hi:[1,0,1]
	v_pk_fma_f32 v[66:67], v[6:7], v[26:27], v[66:67] op_sel_hi:[1,0,1]
	v_pk_fma_f32 v[34:35], v[8:9], v[26:27], v[34:35] op_sel:[0,1,0]
	v_pk_fma_f32 v[36:37], v[6:7], v[26:27], v[36:37] op_sel:[0,1,0]
	v_pk_fma_f32 v[68:69], v[8:9], v[28:29], v[68:69] op_sel_hi:[1,0,1]
	v_pk_fma_f32 v[70:71], v[6:7], v[28:29], v[70:71] op_sel_hi:[1,0,1]
	v_mov_b32_e32 v72, v29
	global_load_dwordx4 v[26:29], v[38:39], off nt
	s_mov_b32 s14, 0xfffb8000
	v_add_co_u32_e32 v74, vcc, s14, v56
	v_pk_fma_f32 v[38:39], v[8:9], v[44:45], v[2:3] op_sel_hi:[1,0,1]
	s_nop 0
	v_addc_co_u32_e32 v75, vcc, -1, v57, vcc
	v_pk_fma_f32 v[44:45], v[6:7], v[44:45], v[4:5] op_sel_hi:[1,0,1]
	global_load_dwordx4 v[2:5], v[74:75], off nt
	s_waitcnt lgkmcnt(0)
	v_pk_fma_f32 v[14:15], v[8:9], v[30:31], v[14:15] op_sel_hi:[1,0,1]
	v_pk_fma_f32 v[16:17], v[6:7], v[30:31], v[16:17] op_sel_hi:[1,0,1]
	v_pk_fma_f32 v[18:19], v[8:9], v[30:31], v[18:19] op_sel:[0,1,0]
	v_pk_fma_f32 v[20:21], v[6:7], v[30:31], v[20:21] op_sel:[0,1,0]
	v_mov_b32_e32 v30, v33
	v_pk_fma_f32 v[22:23], v[8:9], v[32:33], v[22:23] op_sel_hi:[1,0,1]
	v_pk_fma_f32 v[24:25], v[6:7], v[32:33], v[24:25] op_sel_hi:[1,0,1]
	v_pk_fma_f32 v[74:75], v[8:9], v[72:73], v[10:11] op_sel_hi:[1,0,1]
	v_pk_fma_f32 v[72:73], v[6:7], v[72:73], v[12:13] op_sel_hi:[1,0,1]
	v_pk_fma_f32 v[40:41], v[8:9], v[30:31], v[40:41] op_sel_hi:[1,0,1]
	v_pk_fma_f32 v[42:43], v[6:7], v[30:31], v[42:43] op_sel_hi:[1,0,1]
	ds_read_b128 v[6:9], v77 offset:384
	ds_read_b128 v[10:13], v77 offset:400
	s_mov_b32 s14, 0xfffc4000
	s_waitcnt lgkmcnt(1)
	v_mov_b32_e32 v78, v9
	s_waitcnt lgkmcnt(0)
	v_mov_b32_e32 v80, v13
	s_waitcnt vmcnt(1)
	v_pk_fma_f32 v[46:47], v[28:29], v[6:7], v[46:47] op_sel_hi:[1,0,1]
	v_pk_fma_f32 v[48:49], v[26:27], v[6:7], v[48:49] op_sel_hi:[1,0,1]
	v_pk_fma_f32 v[50:51], v[28:29], v[6:7], v[50:51] op_sel:[0,1,0]
	v_pk_fma_f32 v[58:59], v[26:27], v[6:7], v[58:59] op_sel:[0,1,0]
	v_pk_fma_f32 v[60:61], v[28:29], v[8:9], v[60:61] op_sel_hi:[1,0,1]
	v_pk_fma_f32 v[62:63], v[26:27], v[8:9], v[62:63] op_sel_hi:[1,0,1]
	ds_read_b128 v[6:9], v77 offset:416
	ds_read_b128 v[30:33], v77 offset:432
	v_pk_fma_f32 v[64:65], v[28:29], v[10:11], v[64:65] op_sel_hi:[1,0,1]
	v_pk_fma_f32 v[66:67], v[26:27], v[10:11], v[66:67] op_sel_hi:[1,0,1]
	v_pk_fma_f32 v[34:35], v[28:29], v[10:11], v[34:35] op_sel:[0,1,0]
	s_waitcnt lgkmcnt(1)
	v_mov_b32_e32 v82, v9
	v_pk_fma_f32 v[36:37], v[26:27], v[10:11], v[36:37] op_sel:[0,1,0]
	v_pk_fma_f32 v[68:69], v[28:29], v[12:13], v[68:69] op_sel_hi:[1,0,1]
	v_pk_fma_f32 v[70:71], v[26:27], v[12:13], v[70:71] op_sel_hi:[1,0,1]
	v_pk_fma_f32 v[14:15], v[28:29], v[6:7], v[14:15] op_sel_hi:[1,0,1]
	v_pk_fma_f32 v[16:17], v[26:27], v[6:7], v[16:17] op_sel_hi:[1,0,1]
	v_pk_fma_f32 v[18:19], v[28:29], v[6:7], v[18:19] op_sel:[0,1,0]
	v_pk_fma_f32 v[20:21], v[26:27], v[6:7], v[20:21] op_sel:[0,1,0]
	v_pk_fma_f32 v[22:23], v[28:29], v[8:9], v[22:23] op_sel_hi:[1,0,1]
	v_pk_fma_f32 v[24:25], v[26:27], v[8:9], v[24:25] op_sel_hi:[1,0,1]
	v_pk_fma_f32 v[6:7], v[28:29], v[78:79], v[38:39] op_sel_hi:[1,0,1]
	v_pk_fma_f32 v[8:9], v[26:27], v[78:79], v[44:45] op_sel_hi:[1,0,1]
	v_pk_fma_f32 v[10:11], v[28:29], v[80:81], v[74:75] op_sel_hi:[1,0,1]
	v_pk_fma_f32 v[12:13], v[26:27], v[80:81], v[72:73] op_sel_hi:[1,0,1]
	v_pk_fma_f32 v[40:41], v[28:29], v[82:83], v[40:41] op_sel_hi:[1,0,1]
	v_pk_fma_f32 v[42:43], v[26:27], v[82:83], v[42:43] op_sel_hi:[1,0,1]
	ds_read_b128 v[26:29], v77 offset:448
	v_add_co_u32_e32 v38, vcc, s14, v56
	s_waitcnt lgkmcnt(1)
	v_mov_b32_e32 v44, v33
	v_addc_co_u32_e32 v39, vcc, -1, v57, vcc
	s_waitcnt vmcnt(0)
	v_pk_fma_f32 v[46:47], v[4:5], v[30:31], v[46:47] op_sel_hi:[1,0,1]
	v_pk_fma_f32 v[48:49], v[2:3], v[30:31], v[48:49] op_sel_hi:[1,0,1]
	v_pk_fma_f32 v[50:51], v[4:5], v[30:31], v[50:51] op_sel:[0,1,0]
	v_pk_fma_f32 v[58:59], v[2:3], v[30:31], v[58:59] op_sel:[0,1,0]
	v_pk_fma_f32 v[60:61], v[4:5], v[32:33], v[60:61] op_sel_hi:[1,0,1]
	v_pk_fma_f32 v[62:63], v[2:3], v[32:33], v[62:63] op_sel_hi:[1,0,1]
	ds_read_b128 v[30:33], v77 offset:464
	s_waitcnt lgkmcnt(1)
	v_pk_fma_f32 v[64:65], v[4:5], v[26:27], v[64:65] op_sel_hi:[1,0,1]
	v_pk_fma_f32 v[66:67], v[2:3], v[26:27], v[66:67] op_sel_hi:[1,0,1]
	v_pk_fma_f32 v[34:35], v[4:5], v[26:27], v[34:35] op_sel:[0,1,0]
	v_pk_fma_f32 v[36:37], v[2:3], v[26:27], v[36:37] op_sel:[0,1,0]
	v_pk_fma_f32 v[68:69], v[4:5], v[28:29], v[68:69] op_sel_hi:[1,0,1]
	v_pk_fma_f32 v[70:71], v[2:3], v[28:29], v[70:71] op_sel_hi:[1,0,1]
	v_mov_b32_e32 v72, v29
	global_load_dwordx4 v[26:29], v[38:39], off nt
	s_mov_b32 s14, 0xfffd0000
	v_add_co_u32_e32 v74, vcc, s14, v56
	v_pk_fma_f32 v[38:39], v[4:5], v[44:45], v[6:7] op_sel_hi:[1,0,1]
	s_nop 0
	v_addc_co_u32_e32 v75, vcc, -1, v57, vcc
	v_pk_fma_f32 v[44:45], v[2:3], v[44:45], v[8:9] op_sel_hi:[1,0,1]
	global_load_dwordx4 v[6:9], v[74:75], off nt
	s_waitcnt lgkmcnt(0)
	v_pk_fma_f32 v[14:15], v[4:5], v[30:31], v[14:15] op_sel_hi:[1,0,1]
	v_pk_fma_f32 v[16:17], v[2:3], v[30:31], v[16:17] op_sel_hi:[1,0,1]
	v_pk_fma_f32 v[18:19], v[4:5], v[30:31], v[18:19] op_sel:[0,1,0]
	v_pk_fma_f32 v[20:21], v[2:3], v[30:31], v[20:21] op_sel:[0,1,0]
	v_mov_b32_e32 v30, v33
	v_pk_fma_f32 v[22:23], v[4:5], v[32:33], v[22:23] op_sel_hi:[1,0,1]
	v_pk_fma_f32 v[24:25], v[2:3], v[32:33], v[24:25] op_sel_hi:[1,0,1]
	v_pk_fma_f32 v[74:75], v[4:5], v[72:73], v[10:11] op_sel_hi:[1,0,1]
	v_pk_fma_f32 v[72:73], v[2:3], v[72:73], v[12:13] op_sel_hi:[1,0,1]
	v_pk_fma_f32 v[40:41], v[4:5], v[30:31], v[40:41] op_sel_hi:[1,0,1]
	v_pk_fma_f32 v[42:43], v[2:3], v[30:31], v[42:43] op_sel_hi:[1,0,1]
	ds_read_b128 v[2:5], v77 offset:480
	ds_read_b128 v[10:13], v77 offset:496
	s_mov_b32 s14, 0xfffdc000
	s_waitcnt lgkmcnt(1)
	v_mov_b32_e32 v78, v5
	s_waitcnt lgkmcnt(0)
	v_mov_b32_e32 v80, v13
	s_waitcnt vmcnt(1)
	v_pk_fma_f32 v[46:47], v[28:29], v[2:3], v[46:47] op_sel_hi:[1,0,1]
	v_pk_fma_f32 v[48:49], v[26:27], v[2:3], v[48:49] op_sel_hi:[1,0,1]
	v_pk_fma_f32 v[50:51], v[28:29], v[2:3], v[50:51] op_sel:[0,1,0]
	v_pk_fma_f32 v[58:59], v[26:27], v[2:3], v[58:59] op_sel:[0,1,0]
	v_pk_fma_f32 v[60:61], v[28:29], v[4:5], v[60:61] op_sel_hi:[1,0,1]
	v_pk_fma_f32 v[62:63], v[26:27], v[4:5], v[62:63] op_sel_hi:[1,0,1]
	ds_read_b128 v[2:5], v77 offset:512
	ds_read_b128 v[30:33], v77 offset:528
	v_pk_fma_f32 v[64:65], v[28:29], v[10:11], v[64:65] op_sel_hi:[1,0,1]
	v_pk_fma_f32 v[66:67], v[26:27], v[10:11], v[66:67] op_sel_hi:[1,0,1]
	v_pk_fma_f32 v[34:35], v[28:29], v[10:11], v[34:35] op_sel:[0,1,0]
	s_waitcnt lgkmcnt(1)
	v_mov_b32_e32 v82, v5
	v_pk_fma_f32 v[36:37], v[26:27], v[10:11], v[36:37] op_sel:[0,1,0]
	v_pk_fma_f32 v[68:69], v[28:29], v[12:13], v[68:69] op_sel_hi:[1,0,1]
	v_pk_fma_f32 v[70:71], v[26:27], v[12:13], v[70:71] op_sel_hi:[1,0,1]
	v_pk_fma_f32 v[14:15], v[28:29], v[2:3], v[14:15] op_sel_hi:[1,0,1]
	v_pk_fma_f32 v[16:17], v[26:27], v[2:3], v[16:17] op_sel_hi:[1,0,1]
	v_pk_fma_f32 v[18:19], v[28:29], v[2:3], v[18:19] op_sel:[0,1,0]
	v_pk_fma_f32 v[20:21], v[26:27], v[2:3], v[20:21] op_sel:[0,1,0]
	v_pk_fma_f32 v[22:23], v[28:29], v[4:5], v[22:23] op_sel_hi:[1,0,1]
	v_pk_fma_f32 v[24:25], v[26:27], v[4:5], v[24:25] op_sel_hi:[1,0,1]
	v_pk_fma_f32 v[10:11], v[28:29], v[78:79], v[38:39] op_sel_hi:[1,0,1]
	v_pk_fma_f32 v[12:13], v[26:27], v[78:79], v[44:45] op_sel_hi:[1,0,1]
	v_pk_fma_f32 v[2:3], v[28:29], v[80:81], v[74:75] op_sel_hi:[1,0,1]
	v_pk_fma_f32 v[4:5], v[26:27], v[80:81], v[72:73] op_sel_hi:[1,0,1]
	v_pk_fma_f32 v[40:41], v[28:29], v[82:83], v[40:41] op_sel_hi:[1,0,1]
	v_pk_fma_f32 v[42:43], v[26:27], v[82:83], v[42:43] op_sel_hi:[1,0,1]
	ds_read_b128 v[26:29], v77 offset:544
	s_waitcnt lgkmcnt(1)
	v_mov_b32_e32 v44, v33
	s_waitcnt vmcnt(0)
	v_pk_fma_f32 v[46:47], v[8:9], v[30:31], v[46:47] op_sel_hi:[1,0,1]
	v_pk_fma_f32 v[48:49], v[6:7], v[30:31], v[48:49] op_sel_hi:[1,0,1]
	v_pk_fma_f32 v[50:51], v[8:9], v[30:31], v[50:51] op_sel:[0,1,0]
	v_pk_fma_f32 v[58:59], v[6:7], v[30:31], v[58:59] op_sel:[0,1,0]
	v_pk_fma_f32 v[60:61], v[8:9], v[32:33], v[60:61] op_sel_hi:[1,0,1]
	v_pk_fma_f32 v[62:63], v[6:7], v[32:33], v[62:63] op_sel_hi:[1,0,1]
	ds_read_b128 v[30:33], v77 offset:560
	v_add_co_u32_e32 v38, vcc, s14, v56
	s_mov_b32 s14, 0xfffe8000
	s_nop 0
	v_addc_co_u32_e32 v39, vcc, -1, v57, vcc
	s_waitcnt lgkmcnt(0)
	v_pk_fma_f32 v[72:73], v[8:9], v[30:31], v[14:15] op_sel_hi:[1,0,1]
	v_pk_fma_f32 v[74:75], v[6:7], v[30:31], v[16:17] op_sel_hi:[1,0,1]
	global_load_dwordx4 v[14:17], v[38:39], off nt
	v_pk_fma_f32 v[64:65], v[8:9], v[26:27], v[64:65] op_sel_hi:[1,0,1]
	v_pk_fma_f32 v[66:67], v[6:7], v[26:27], v[66:67] op_sel_hi:[1,0,1]
	v_pk_fma_f32 v[34:35], v[8:9], v[26:27], v[34:35] op_sel:[0,1,0]
	v_pk_fma_f32 v[26:27], v[6:7], v[26:27], v[36:37] op_sel:[0,1,0]
	v_pk_fma_f32 v[36:37], v[8:9], v[28:29], v[68:69] op_sel_hi:[1,0,1]
	v_pk_fma_f32 v[68:69], v[6:7], v[28:29], v[70:71] op_sel_hi:[1,0,1]
	v_add_co_u32_e32 v70, vcc, s14, v56
	v_pk_fma_f32 v[18:19], v[8:9], v[30:31], v[18:19] op_sel:[0,1,0]
	s_nop 0
	v_addc_co_u32_e32 v71, vcc, -1, v57, vcc
	v_pk_fma_f32 v[20:21], v[6:7], v[30:31], v[20:21] op_sel:[0,1,0]
	v_pk_fma_f32 v[22:23], v[8:9], v[32:33], v[22:23] op_sel_hi:[1,0,1]
	v_pk_fma_f32 v[24:25], v[6:7], v[32:33], v[24:25] op_sel_hi:[1,0,1]
	v_mov_b32_e32 v30, v33
	v_pk_fma_f32 v[32:33], v[8:9], v[44:45], v[10:11] op_sel_hi:[1,0,1]
	v_pk_fma_f32 v[38:39], v[6:7], v[44:45], v[12:13] op_sel_hi:[1,0,1]
	global_load_dwordx4 v[10:13], v[70:71], off nt
	v_mov_b32_e32 v28, v29
	v_pk_fma_f32 v[44:45], v[8:9], v[28:29], v[2:3] op_sel_hi:[1,0,1]
	v_pk_fma_f32 v[28:29], v[6:7], v[28:29], v[4:5] op_sel_hi:[1,0,1]
	v_pk_fma_f32 v[40:41], v[8:9], v[30:31], v[40:41] op_sel_hi:[1,0,1]
	v_pk_fma_f32 v[30:31], v[6:7], v[30:31], v[42:43] op_sel_hi:[1,0,1]
	ds_read_b128 v[2:5], v77 offset:576
	ds_read_b128 v[6:9], v77 offset:592
	s_mov_b32 s14, 0xffff4000
	s_waitcnt lgkmcnt(0)
	v_mov_b32_e32 v70, v9
	s_waitcnt vmcnt(1)
	v_pk_fma_f32 v[42:43], v[16:17], v[2:3], v[46:47] op_sel_hi:[1,0,1]
	v_pk_fma_f32 v[46:47], v[14:15], v[2:3], v[48:49] op_sel_hi:[1,0,1]
	v_pk_fma_f32 v[48:49], v[16:17], v[2:3], v[50:51] op_sel:[0,1,0]
	v_pk_fma_f32 v[50:51], v[14:15], v[2:3], v[58:59] op_sel:[0,1,0]
	v_pk_fma_f32 v[58:59], v[16:17], v[4:5], v[60:61] op_sel_hi:[1,0,1]
	v_pk_fma_f32 v[60:61], v[14:15], v[4:5], v[62:63] op_sel_hi:[1,0,1]
	v_mov_b32_e32 v62, v5
	v_pk_fma_f32 v[64:65], v[16:17], v[6:7], v[64:65] op_sel_hi:[1,0,1]
	v_pk_fma_f32 v[66:67], v[14:15], v[6:7], v[66:67] op_sel_hi:[1,0,1]
	v_pk_fma_f32 v[34:35], v[16:17], v[6:7], v[34:35] op_sel:[0,1,0]
	v_pk_fma_f32 v[26:27], v[14:15], v[6:7], v[26:27] op_sel:[0,1,0]
	v_pk_fma_f32 v[36:37], v[16:17], v[8:9], v[36:37] op_sel_hi:[1,0,1]
	v_pk_fma_f32 v[68:69], v[14:15], v[8:9], v[68:69] op_sel_hi:[1,0,1]
	ds_read_b128 v[2:5], v77 offset:608
	ds_read_b128 v[6:9], v77 offset:624
	v_pk_fma_f32 v[32:33], v[16:17], v[62:63], v[32:33] op_sel_hi:[1,0,1]
	v_pk_fma_f32 v[38:39], v[14:15], v[62:63], v[38:39] op_sel_hi:[1,0,1]
	v_add_co_u32_e32 v62, vcc, s14, v56
	v_pk_fma_f32 v[44:45], v[16:17], v[70:71], v[44:45] op_sel_hi:[1,0,1]
	s_nop 0
	v_addc_co_u32_e32 v63, vcc, -1, v57, vcc
	v_pk_fma_f32 v[28:29], v[14:15], v[70:71], v[28:29] op_sel_hi:[1,0,1]
	s_waitcnt lgkmcnt(0)
	v_mov_b32_e32 v70, v9
	s_waitcnt vmcnt(0)
	v_pk_fma_f32 v[42:43], v[12:13], v[6:7], v[42:43] op_sel_hi:[1,0,1]
	v_pk_fma_f32 v[46:47], v[10:11], v[6:7], v[46:47] op_sel_hi:[1,0,1]
	v_pk_fma_f32 v[48:49], v[12:13], v[6:7], v[48:49] op_sel:[0,1,0]
	v_pk_fma_f32 v[50:51], v[10:11], v[6:7], v[50:51] op_sel:[0,1,0]
	v_pk_fma_f32 v[58:59], v[12:13], v[8:9], v[58:59] op_sel_hi:[1,0,1]
	v_pk_fma_f32 v[78:79], v[10:11], v[8:9], v[60:61] op_sel_hi:[1,0,1]
	global_load_dwordx4 v[6:9], v[62:63], off nt
	v_pk_fma_f32 v[72:73], v[16:17], v[2:3], v[72:73] op_sel_hi:[1,0,1]
	v_pk_fma_f32 v[74:75], v[14:15], v[2:3], v[74:75] op_sel_hi:[1,0,1]
	v_pk_fma_f32 v[18:19], v[16:17], v[2:3], v[18:19] op_sel:[0,1,0]
	v_pk_fma_f32 v[20:21], v[14:15], v[2:3], v[20:21] op_sel:[0,1,0]
	v_mov_b32_e32 v2, v5
	v_pk_fma_f32 v[22:23], v[16:17], v[4:5], v[22:23] op_sel_hi:[1,0,1]
	v_pk_fma_f32 v[24:25], v[14:15], v[4:5], v[24:25] op_sel_hi:[1,0,1]
	v_pk_fma_f32 v[40:41], v[16:17], v[2:3], v[40:41] op_sel_hi:[1,0,1]
	v_pk_fma_f32 v[30:31], v[14:15], v[2:3], v[30:31] op_sel_hi:[1,0,1]
	ds_read_b128 v[2:5], v77 offset:640
	ds_read_b128 v[14:17], v77 offset:656
	v_pk_fma_f32 v[86:87], v[12:13], v[70:71], v[32:33] op_sel_hi:[1,0,1]
	v_pk_fma_f32 v[70:71], v[10:11], v[70:71], v[38:39] op_sel_hi:[1,0,1]
	s_mov_b64 s[14:15], 0xc0000
	s_waitcnt lgkmcnt(1)
	v_pk_fma_f32 v[80:81], v[12:13], v[2:3], v[64:65] op_sel_hi:[1,0,1]
	v_pk_fma_f32 v[66:67], v[10:11], v[2:3], v[66:67] op_sel_hi:[1,0,1]
	v_pk_fma_f32 v[34:35], v[12:13], v[2:3], v[34:35] op_sel:[0,1,0]
	v_pk_fma_f32 v[82:83], v[10:11], v[2:3], v[26:27] op_sel:[0,1,0]
	v_pk_fma_f32 v[84:85], v[12:13], v[4:5], v[36:37] op_sel_hi:[1,0,1]
	v_pk_fma_f32 v[68:69], v[10:11], v[4:5], v[68:69] op_sel_hi:[1,0,1]
	v_mov_b32_e32 v26, v5
	ds_read_b128 v[2:5], v77 offset:672
	s_waitcnt lgkmcnt(1)
	v_mov_b32_e32 v32, v17
	v_pk_fma_f32 v[92:93], v[12:13], v[14:15], v[18:19] op_sel:[0,1,0]
	v_pk_fma_f32 v[96:97], v[12:13], v[16:17], v[22:23] op_sel_hi:[1,0,1]
	v_pk_fma_f32 v[98:99], v[10:11], v[16:17], v[24:25] op_sel_hi:[1,0,1]
	ds_read_b128 v[16:19], v77 offset:688
	ds_read_b128 v[60:63], v77 offset:704
	v_pk_fma_f32 v[88:89], v[12:13], v[14:15], v[72:73] op_sel_hi:[1,0,1]
	v_pk_fma_f32 v[90:91], v[10:11], v[14:15], v[74:75] op_sel_hi:[1,0,1]
	v_pk_fma_f32 v[94:95], v[10:11], v[14:15], v[20:21] op_sel:[0,1,0]
	v_pk_fma_f32 v[20:21], v[12:13], v[26:27], v[44:45] op_sel_hi:[1,0,1]
	v_pk_fma_f32 v[22:23], v[10:11], v[26:27], v[28:29] op_sel_hi:[1,0,1]
	v_pk_fma_f32 v[24:25], v[12:13], v[32:33], v[40:41] op_sel_hi:[1,0,1]
	v_pk_fma_f32 v[26:27], v[10:11], v[32:33], v[30:31] op_sel_hi:[1,0,1]
	s_waitcnt lgkmcnt(1)
	v_mov_b32_e32 v64, v19
	s_waitcnt vmcnt(0)
	v_pk_fma_f32 v[10:11], v[8:9], v[2:3], v[42:43] op_sel_hi:[1,0,1]
	v_pk_fma_f32 v[12:13], v[6:7], v[2:3], v[46:47] op_sel_hi:[1,0,1]
	v_pk_fma_f32 v[14:15], v[8:9], v[2:3], v[48:49] op_sel:[0,1,0]
	v_pk_fma_f32 v[30:31], v[6:7], v[2:3], v[50:51] op_sel:[0,1,0]
	v_mov_b32_e32 v2, v5
	v_pk_fma_f32 v[72:73], v[8:9], v[4:5], v[58:59] op_sel_hi:[1,0,1]
	v_pk_fma_f32 v[74:75], v[6:7], v[4:5], v[78:79] op_sel_hi:[1,0,1]
	v_pk_fma_f32 v[38:39], v[8:9], v[16:17], v[34:35] op_sel:[0,1,0]
	v_pk_fma_f32 v[28:29], v[8:9], v[2:3], v[86:87] op_sel_hi:[1,0,1]
	v_pk_fma_f32 v[34:35], v[6:7], v[2:3], v[70:71] op_sel_hi:[1,0,1]
	global_load_dwordx4 v[2:5], v[56:57], off nt
	v_pk_fma_f32 v[36:37], v[6:7], v[16:17], v[66:67] op_sel_hi:[1,0,1]
	s_waitcnt lgkmcnt(0)
	v_mov_b32_e32 v66, v63
	v_pk_fma_f32 v[32:33], v[8:9], v[16:17], v[80:81] op_sel_hi:[1,0,1]
	v_pk_fma_f32 v[40:41], v[6:7], v[16:17], v[82:83] op_sel:[0,1,0]
	v_pk_fma_f32 v[42:43], v[8:9], v[18:19], v[84:85] op_sel_hi:[1,0,1]
	v_pk_fma_f32 v[44:45], v[6:7], v[18:19], v[68:69] op_sel_hi:[1,0,1]
	ds_read_b128 v[16:19], v77 offset:720
	v_pk_fma_f32 v[68:69], v[8:9], v[64:65], v[20:21] op_sel_hi:[1,0,1]
	v_pk_fma_f32 v[70:71], v[6:7], v[64:65], v[22:23] op_sel_hi:[1,0,1]
	v_pk_fma_f32 v[64:65], v[8:9], v[66:67], v[24:25] op_sel_hi:[1,0,1]
	v_pk_fma_f32 v[66:67], v[6:7], v[66:67], v[26:27] op_sel_hi:[1,0,1]
	ds_read_b128 v[20:23], v77 offset:736
	ds_read_b128 v[24:27], v77 offset:752
	v_pk_fma_f32 v[46:47], v[8:9], v[60:61], v[88:89] op_sel_hi:[1,0,1]
	v_pk_fma_f32 v[48:49], v[6:7], v[60:61], v[90:91] op_sel_hi:[1,0,1]
	v_pk_fma_f32 v[50:51], v[8:9], v[60:61], v[92:93] op_sel:[0,1,0]
	v_pk_fma_f32 v[58:59], v[6:7], v[60:61], v[94:95] op_sel:[0,1,0]
	v_pk_fma_f32 v[60:61], v[8:9], v[62:63], v[96:97] op_sel_hi:[1,0,1]
	v_pk_fma_f32 v[62:63], v[6:7], v[62:63], v[98:99] op_sel_hi:[1,0,1]
	v_lshl_add_u64 v[56:57], v[56:57], 0, s[14:15]
	s_waitcnt vmcnt(0) lgkmcnt(2)
	v_pk_fma_f32 v[8:9], v[4:5], v[16:17], v[10:11] op_sel_hi:[1,0,1]
	v_pk_fma_f32 v[6:7], v[2:3], v[16:17], v[12:13] op_sel_hi:[1,0,1]
	v_pk_fma_f32 v[12:13], v[4:5], v[16:17], v[14:15] op_sel:[0,1,0]
	v_pk_fma_f32 v[10:11], v[2:3], v[16:17], v[30:31] op_sel:[0,1,0]
	v_pk_fma_f32 v[16:17], v[4:5], v[18:19], v[72:73] op_sel_hi:[1,0,1]
	v_pk_fma_f32 v[14:15], v[2:3], v[18:19], v[74:75] op_sel_hi:[1,0,1]
	v_mov_b32_e32 v18, v19
	s_waitcnt lgkmcnt(1)
	v_mov_b32_e32 v72, v23
	s_waitcnt lgkmcnt(0)
	v_mov_b32_e32 v74, v27
	v_pk_fma_f32 v[30:31], v[4:5], v[18:19], v[28:29] op_sel_hi:[1,0,1]
	v_pk_fma_f32 v[28:29], v[2:3], v[18:19], v[34:35] op_sel_hi:[1,0,1]
	v_pk_fma_f32 v[34:35], v[4:5], v[20:21], v[32:33] op_sel_hi:[1,0,1]
	v_pk_fma_f32 v[32:33], v[2:3], v[20:21], v[36:37] op_sel_hi:[1,0,1]
	v_pk_fma_f32 v[38:39], v[4:5], v[20:21], v[38:39] op_sel:[0,1,0]
	v_pk_fma_f32 v[36:37], v[2:3], v[20:21], v[40:41] op_sel:[0,1,0]
	v_pk_fma_f32 v[20:21], v[4:5], v[22:23], v[42:43] op_sel_hi:[1,0,1]
	v_pk_fma_f32 v[18:19], v[2:3], v[22:23], v[44:45] op_sel_hi:[1,0,1]
	v_pk_fma_f32 v[42:43], v[4:5], v[72:73], v[68:69] op_sel_hi:[1,0,1]
	v_pk_fma_f32 v[40:41], v[2:3], v[72:73], v[70:71] op_sel_hi:[1,0,1]
	v_pk_fma_f32 v[46:47], v[4:5], v[24:25], v[46:47] op_sel_hi:[1,0,1]
	v_pk_fma_f32 v[44:45], v[2:3], v[24:25], v[48:49] op_sel_hi:[1,0,1]
	v_pk_fma_f32 v[50:51], v[4:5], v[24:25], v[50:51] op_sel:[0,1,0]
	v_pk_fma_f32 v[48:49], v[2:3], v[24:25], v[58:59] op_sel:[0,1,0]
	v_pk_fma_f32 v[24:25], v[4:5], v[26:27], v[60:61] op_sel_hi:[1,0,1]
	v_pk_fma_f32 v[22:23], v[2:3], v[26:27], v[62:63] op_sel_hi:[1,0,1]
	v_pk_fma_f32 v[4:5], v[4:5], v[74:75], v[64:65] op_sel_hi:[1,0,1]
	v_pk_fma_f32 v[2:3], v[2:3], v[74:75], v[66:67] op_sel_hi:[1,0,1]
	s_cbranch_scc0 .LBB0_34
	s_barrier
	ds_write_b128 v76, v[6:9]
	ds_write_b128 v76, v[10:13] offset:1024
	ds_write_b128 v76, v[14:17] offset:2048
	ds_write_b128 v76, v[28:31] offset:3072
	ds_write_b128 v76, v[32:35] offset:4096
	ds_write_b128 v76, v[36:39] offset:5120
	ds_write_b128 v76, v[18:21] offset:6144
	ds_write_b128 v76, v[40:43] offset:7168
	ds_write_b128 v76, v[44:47] offset:8192
	ds_write_b128 v76, v[48:51] offset:9216
	ds_write_b128 v76, v[22:25] offset:10240
	ds_write_b128 v76, v[2:5] offset:11264
	s_waitcnt lgkmcnt(0)
	s_barrier
	s_and_saveexec_b64 s[14:15], s[4:5]
	v_readlane_b32 s36, v250, 37
	v_readlane_b32 s40, v250, 41
	v_readlane_b32 s41, v250, 42
	v_readlane_b32 s37, v250, 38
	v_readlane_b32 s38, v250, 39
	v_readlane_b32 s39, v250, 40
	v_readlane_b32 s42, v250, 43
	v_readlane_b32 s43, v250, 44
	v_readlane_b32 s44, v250, 45
	v_readlane_b32 s45, v250, 46
	v_readlane_b32 s46, v250, 47
	v_readlane_b32 s47, v250, 48
	v_readlane_b32 s48, v250, 49
	v_readlane_b32 s49, v250, 50
	v_readlane_b32 s50, v250, 51
	v_readlane_b32 s51, v250, 52
	s_cbranch_execz .LBB0_23
	s_lshl_b64 s[16:17], s[12:13], 2
	s_add_u32 s16, s20, s16
	s_addc_u32 s17, s21, s17
	v_lshl_add_u32 v2, v1, 2, 0
	s_mov_b64 s[18:19], 0
	v_mov_b32_e32 v3, v1

.LBB0_96:
	s_ashr_i32 s3, s4, 31
	s_mul_hi_u32 s30, s20, s4
	s_mul_i32 s3, s20, s3
	s_add_i32 s31, s30, s3
	s_mul_i32 s30, s20, s4
	s_lshl_b64 s[30:31], s[30:31], 2
	s_add_u32 s40, s40, s30
	s_addc_u32 s41, s41, s31
	s_ashr_i32 s3, s2, 31
	s_lshl_b64 s[30:31], s[2:3], 2
	s_add_u32 s30, s40, s30
	s_waitcnt vmcnt(0)
	v_mul_lo_u32 v2, s20, v1
	s_addc_u32 s31, s41, s31
	v_or_b32_e32 v2, v2, v54
	v_mov_b32_e32 v3, v51
	v_lshl_add_u64 v[26:27], v[2:3], 2, s[30:31]
	s_lshl_b32 s30, s20, 5
	s_mov_b32 s31, s21
	v_lshl_add_u64 v[10:11], s[30:31], 2, v[26:27]
	s_mul_i32 s30, s20, 33
	v_lshl_add_u64 v[14:15], s[30:31], 2, v[26:27]
	s_lshl_b32 s30, s20, 6
	v_lshl_add_u64 v[18:19], s[30:31], 2, v[26:27]
	s_mul_i32 s30, s20, 0x41
	v_lshl_add_u64 v[6:7], s[20:21], 2, v[26:27]
	v_lshl_add_u64 v[22:23], s[30:31], 2, v[26:27]
	s_mul_i32 s30, s20, 0x60
	s_mulk_i32 s20, 0x61
	v_lshl_add_u64 v[28:29], s[30:31], 2, v[26:27]
	v_lshl_add_u64 v[30:31], s[20:21], 2, v[26:27]
	flat_load_dwordx4 v[2:5], v[26:27] nt
	s_nop 0
	flat_load_dwordx4 v[6:9], v[6:7] nt
	s_nop 0
	flat_load_dwordx4 v[10:13], v[10:11] nt
	s_nop 0
	flat_load_dwordx4 v[14:17], v[14:15] nt
	s_nop 0
	flat_load_dwordx4 v[18:21], v[18:19] nt
	s_nop 0
	flat_load_dwordx4 v[22:25], v[22:23] nt
	s_nop 0
	flat_load_dwordx4 v[26:29], v[28:29] nt
	s_nop 0
	flat_load_dwordx4 v[30:33], v[30:31] nt

.LBB0_110:
	s_ashr_i32 s5, s41, 31
	s_mul_hi_u32 s44, s41, s20
	s_mul_i32 s5, s5, s20
	s_add_i32 s45, s44, s5
	s_mul_i32 s44, s41, s20
	s_lshl_b64 s[44:45], s[44:45], 2
	s_add_u32 s5, s42, s44
	s_addc_u32 s42, s43, s45
	s_ashr_i32 s41, s40, 31
	s_lshl_b64 s[40:41], s[40:41], 2
	s_add_u32 s40, s5, s40
	v_mul_lo_u32 v2, s20, v1
	s_addc_u32 s41, s42, s41
	v_or_b32_e32 v2, v2, v54
	v_mov_b32_e32 v3, v51
	v_lshl_add_u64 v[26:27], v[2:3], 2, s[40:41]
	s_lshl_b32 s40, s20, 5
	s_mov_b32 s41, s21
	v_lshl_add_u64 v[10:11], s[40:41], 2, v[26:27]
	s_mul_i32 s40, s20, 33
	v_lshl_add_u64 v[14:15], s[40:41], 2, v[26:27]
	s_lshl_b32 s40, s20, 6
	v_lshl_add_u64 v[18:19], s[40:41], 2, v[26:27]
	s_mul_i32 s40, s20, 0x41
	v_lshl_add_u64 v[6:7], s[20:21], 2, v[26:27]
	v_lshl_add_u64 v[22:23], s[40:41], 2, v[26:27]
	s_mul_i32 s40, s20, 0x60
	s_mulk_i32 s20, 0x61
	v_lshl_add_u64 v[28:29], s[40:41], 2, v[26:27]
	v_lshl_add_u64 v[30:31], s[20:21], 2, v[26:27]
	flat_load_dwordx4 v[2:5], v[26:27] nt
	s_nop 0
	flat_load_dwordx4 v[6:9], v[6:7] nt
	s_nop 0
	flat_load_dwordx4 v[10:13], v[10:11] nt
	s_nop 0
	flat_load_dwordx4 v[14:17], v[14:15] nt
	s_nop 0
	flat_load_dwordx4 v[18:21], v[18:19] nt
	s_nop 0
	flat_load_dwordx4 v[22:25], v[22:23] nt
	s_nop 0
	flat_load_dwordx4 v[26:29], v[28:29] nt
	s_nop 0
	flat_load_dwordx4 v[30:33], v[30:31] nt

.LBB0_418:
	s_ashr_i32 s1, s2, 31
	s_mul_hi_u32 s22, s28, s2
	s_mul_i32 s1, s28, s1
	s_add_i32 s23, s22, s1
	s_mul_i32 s22, s28, s2
	s_lshl_b64 s[22:23], s[22:23], 2
	s_add_u32 s44, s44, s22
	s_addc_u32 s45, s45, s23
	s_ashr_i32 s1, s0, 31
	s_lshl_b64 s[22:23], s[0:1], 2
	s_add_u32 s22, s44, s22
	s_waitcnt vmcnt(0)
	v_mul_lo_u32 v2, s28, v52
	s_addc_u32 s23, s45, s23
	v_or_b32_e32 v2, v2, v53
	v_mov_b32_e32 v3, v67
	v_lshl_add_u64 v[26:27], v[2:3], 2, s[22:23]
	s_lshl_b32 s22, s28, 5
	s_mov_b32 s23, s29
	v_lshl_add_u64 v[10:11], s[22:23], 2, v[26:27]
	s_mul_i32 s22, s28, 33
	v_lshl_add_u64 v[14:15], s[22:23], 2, v[26:27]
	s_lshl_b32 s22, s28, 6
	v_lshl_add_u64 v[18:19], s[22:23], 2, v[26:27]
	s_mul_i32 s22, s28, 0x41
	v_lshl_add_u64 v[6:7], s[28:29], 2, v[26:27]
	v_lshl_add_u64 v[22:23], s[22:23], 2, v[26:27]
	s_mul_i32 s22, s28, 0x60
	s_mulk_i32 s28, 0x61
	v_lshl_add_u64 v[28:29], s[22:23], 2, v[26:27]
	v_lshl_add_u64 v[30:31], s[28:29], 2, v[26:27]
	flat_load_dwordx4 v[2:5], v[26:27] nt
	s_nop 0
	flat_load_dwordx4 v[6:9], v[6:7] nt
	s_nop 0
	flat_load_dwordx4 v[10:13], v[10:11] nt
	s_nop 0
	flat_load_dwordx4 v[14:17], v[14:15] nt
	s_nop 0
	flat_load_dwordx4 v[18:21], v[18:19] nt
	s_nop 0
	flat_load_dwordx4 v[22:25], v[22:23] nt
	s_nop 0
	flat_load_dwordx4 v[26:29], v[28:29] nt
	s_nop 0
	flat_load_dwordx4 v[30:33], v[30:31] nt

.LBB0_432:
	s_ashr_i32 s3, s45, 31
	s_mul_hi_u32 s48, s45, s28
	s_mul_i32 s3, s3, s28
	s_add_i32 s49, s48, s3
	s_mul_i32 s48, s45, s28
	s_lshl_b64 s[48:49], s[48:49], 2
	s_add_u32 s3, s46, s48
	s_addc_u32 s46, s47, s49
	s_ashr_i32 s45, s44, 31
	s_lshl_b64 s[44:45], s[44:45], 2
	s_add_u32 s44, s3, s44
	v_mul_lo_u32 v2, s28, v52
	s_addc_u32 s45, s46, s45
	v_or_b32_e32 v2, v2, v53
	v_mov_b32_e32 v3, v67
	v_lshl_add_u64 v[26:27], v[2:3], 2, s[44:45]
	s_lshl_b32 s44, s28, 5
	s_mov_b32 s45, s29
	v_lshl_add_u64 v[10:11], s[44:45], 2, v[26:27]
	s_mul_i32 s44, s28, 33
	v_lshl_add_u64 v[14:15], s[44:45], 2, v[26:27]
	s_lshl_b32 s44, s28, 6
	v_lshl_add_u64 v[18:19], s[44:45], 2, v[26:27]
	s_mul_i32 s44, s28, 0x41
	v_lshl_add_u64 v[6:7], s[28:29], 2, v[26:27]
	v_lshl_add_u64 v[22:23], s[44:45], 2, v[26:27]
	s_mul_i32 s44, s28, 0x60
	s_mulk_i32 s28, 0x61
	v_lshl_add_u64 v[28:29], s[44:45], 2, v[26:27]
	v_lshl_add_u64 v[30:31], s[28:29], 2, v[26:27]
	flat_load_dwordx4 v[2:5], v[26:27] nt
	s_nop 0
	flat_load_dwordx4 v[6:9], v[6:7] nt
	s_nop 0
	flat_load_dwordx4 v[10:13], v[10:11] nt
	s_nop 0
	flat_load_dwordx4 v[14:17], v[14:15] nt
	s_nop 0
	flat_load_dwordx4 v[18:21], v[18:19] nt
	s_nop 0
	flat_load_dwordx4 v[22:25], v[22:23] nt
	s_nop 0
	flat_load_dwordx4 v[26:29], v[28:29] nt
	s_nop 0
	flat_load_dwordx4 v[30:33], v[30:31] nt

.LBB0_1233:
	v_lshl_add_u64 v[50:51], v[122:123], 0, s[10:11]
	s_mov_b32 s17, 0x6000000
	v_add_co_u32_e32 v52, vcc, s17, v50
	s_mov_b32 s17, 0x600c000
	s_nop 0
	v_addc_co_u32_e32 v53, vcc, 0, v51, vcc
	global_load_dwordx4 v[112:115], v[52:53], off nt
	v_add_co_u32_e32 v52, vcc, s17, v50
	s_mov_b32 s17, 0x6018000
	s_nop 0
	v_addc_co_u32_e32 v53, vcc, 0, v51, vcc
	global_load_dwordx4 v[108:111], v[52:53], off nt
	v_add_co_u32_e32 v52, vcc, s17, v50
	s_mov_b32 s17, 0x6024000
	s_nop 0
	v_addc_co_u32_e32 v53, vcc, 0, v51, vcc
	global_load_dwordx4 v[104:107], v[52:53], off nt
	v_add_co_u32_e32 v52, vcc, s17, v50
	s_mov_b32 s17, 0x6030000
	s_nop 0
	v_addc_co_u32_e32 v53, vcc, 0, v51, vcc
	global_load_dwordx4 v[100:103], v[52:53], off nt
	v_add_co_u32_e32 v52, vcc, s17, v50
	s_mov_b32 s17, 0x603c000
	s_nop 0
	v_addc_co_u32_e32 v53, vcc, 0, v51, vcc
	global_load_dwordx4 v[96:99], v[52:53], off nt
	v_add_co_u32_e32 v52, vcc, s17, v50
	s_mov_b32 s17, 0x6048000
	s_nop 0
	v_addc_co_u32_e32 v53, vcc, 0, v51, vcc
	global_load_dwordx4 v[92:95], v[52:53], off nt
	v_add_co_u32_e32 v52, vcc, s17, v50
	s_mov_b32 s17, 0x6054000
	s_nop 0
	v_addc_co_u32_e32 v53, vcc, 0, v51, vcc
	global_load_dwordx4 v[88:91], v[52:53], off nt
	v_add_co_u32_e32 v52, vcc, s17, v50
	s_mov_b32 s17, 0x6060000
	s_nop 0
	v_addc_co_u32_e32 v53, vcc, 0, v51, vcc
	global_load_dwordx4 v[84:87], v[52:53], off nt
	v_add_co_u32_e32 v52, vcc, s17, v50
	s_mov_b32 s17, 0x606c000
	s_nop 0
	v_addc_co_u32_e32 v53, vcc, 0, v51, vcc
	global_load_dwordx4 v[76:79], v[52:53], off nt
	v_add_co_u32_e32 v52, vcc, s17, v50
	s_mov_b32 s17, 0x6078000
	s_nop 0
	v_addc_co_u32_e32 v53, vcc, 0, v51, vcc
	global_load_dwordx4 v[72:75], v[52:53], off nt
	v_add_co_u32_e32 v52, vcc, s17, v50
	s_mov_b32 s17, 0x6084000
	s_nop 0
	v_addc_co_u32_e32 v53, vcc, 0, v51, vcc
	global_load_dwordx4 v[68:71], v[52:53], off nt
	v_add_co_u32_e32 v52, vcc, s17, v50
	s_mov_b32 s17, 0x6090000
	s_nop 0
	v_addc_co_u32_e32 v53, vcc, 0, v51, vcc
	global_load_dwordx4 v[62:65], v[52:53], off nt
	v_add_co_u32_e32 v52, vcc, s17, v50
	s_mov_b32 s17, 0x609c000
	s_nop 0
	v_addc_co_u32_e32 v53, vcc, 0, v51, vcc
	global_load_dwordx4 v[58:61], v[52:53], off nt
	v_add_co_u32_e32 v52, vcc, s17, v50
	s_mov_b32 s17, 0x60a8000
	s_nop 0
	v_addc_co_u32_e32 v53, vcc, 0, v51, vcc
	v_add_co_u32_e32 v50, vcc, s17, v50
	v_lshl_add_u64 v[80:81], v[120:121], 0, s[10:11]
	s_nop 0
	v_addc_co_u32_e32 v51, vcc, 0, v51, vcc
	v_mov_b32_e32 v125, s5
	global_load_dwordx4 v[54:57], v[52:53], off nt
	s_add_i32 s16, s16, 16
	global_load_dwordx4 v[50:53], v[50:51], off nt
	s_addk_i32 s5, 0x300
	global_load_dwordx4 v[80:83], v[80:81], off nt
	ds_read_b128 v[126:129], v125
	ds_read_b128 v[130:133], v125 offset:16
	ds_read_b128 v[134:137], v125 offset:32
	ds_read_b128 v[138:141], v125 offset:48
	s_add_u32 s10, s10, 0xc0000
	s_waitcnt vmcnt(15) lgkmcnt(3)
	v_pk_fma_f32 v[144:145], v[112:113], v[126:127], v[2:3] op_sel_hi:[1,0,1]
	v_mov_b32_e32 v2, v129
	v_pk_fma_f32 v[16:17], v[114:115], v[2:3], v[16:17] op_sel_hi:[1,0,1]
	v_pk_fma_f32 v[14:15], v[112:113], v[2:3], v[14:15] op_sel_hi:[1,0,1]
	s_waitcnt lgkmcnt(2)
	v_mov_b32_e32 v2, v133
	v_pk_fma_f32 v[32:33], v[114:115], v[2:3], v[32:33] op_sel_hi:[1,0,1]
	v_pk_fma_f32 v[30:31], v[112:113], v[2:3], v[30:31] op_sel_hi:[1,0,1]
	s_waitcnt lgkmcnt(1)
	v_mov_b32_e32 v2, v137
	v_pk_fma_f32 v[142:143], v[114:115], v[126:127], v[4:5] op_sel_hi:[1,0,1]
	v_pk_fma_f32 v[146:147], v[114:115], v[126:127], v[8:9] op_sel:[0,1,0]
	v_pk_fma_f32 v[126:127], v[112:113], v[126:127], v[6:7] op_sel:[0,1,0]
	v_pk_fma_f32 v[48:49], v[114:115], v[2:3], v[48:49] op_sel_hi:[1,0,1]
	v_pk_fma_f32 v[46:47], v[112:113], v[2:3], v[46:47] op_sel_hi:[1,0,1]
	ds_read_b128 v[2:5], v125 offset:64
	ds_read_b128 v[6:9], v125 offset:80
	v_pk_fma_f32 v[20:21], v[114:115], v[130:131], v[20:21] op_sel_hi:[1,0,1]
	v_pk_fma_f32 v[18:19], v[112:113], v[130:131], v[18:19] op_sel_hi:[1,0,1]
	v_pk_fma_f32 v[24:25], v[114:115], v[130:131], v[24:25] op_sel:[0,1,0]
	v_pk_fma_f32 v[22:23], v[112:113], v[130:131], v[22:23] op_sel:[0,1,0]
	v_pk_fma_f32 v[10:11], v[112:113], v[128:129], v[10:11] op_sel_hi:[1,0,1]
	s_waitcnt vmcnt(14) lgkmcnt(1)
	v_pk_fma_f32 v[20:21], v[110:111], v[2:3], v[20:21] op_sel_hi:[1,0,1]
	v_pk_fma_f32 v[18:19], v[108:109], v[2:3], v[18:19] op_sel_hi:[1,0,1]
	v_pk_fma_f32 v[24:25], v[110:111], v[2:3], v[24:25] op_sel:[0,1,0]
	v_pk_fma_f32 v[22:23], v[108:109], v[2:3], v[22:23] op_sel:[0,1,0]
	v_mov_b32_e32 v2, v5
	v_pk_fma_f32 v[12:13], v[114:115], v[128:129], v[12:13] op_sel_hi:[1,0,1]
	v_pk_fma_f32 v[28:29], v[114:115], v[132:133], v[28:29] op_sel_hi:[1,0,1]
	v_pk_fma_f32 v[26:27], v[112:113], v[132:133], v[26:27] op_sel_hi:[1,0,1]
	v_pk_fma_f32 v[36:37], v[114:115], v[134:135], v[36:37] op_sel_hi:[1,0,1]
	v_pk_fma_f32 v[34:35], v[112:113], v[134:135], v[34:35] op_sel_hi:[1,0,1]
	v_pk_fma_f32 v[40:41], v[114:115], v[134:135], v[40:41] op_sel:[0,1,0]
	v_pk_fma_f32 v[38:39], v[112:113], v[134:135], v[38:39] op_sel:[0,1,0]
	v_pk_fma_f32 v[44:45], v[114:115], v[136:137], v[44:45] op_sel_hi:[1,0,1]
	v_pk_fma_f32 v[42:43], v[112:113], v[136:137], v[42:43] op_sel_hi:[1,0,1]
	v_pk_fma_f32 v[132:133], v[108:109], v[140:141], v[10:11] op_sel_hi:[1,0,1]
	v_mov_b32_e32 v10, v141
	v_pk_fma_f32 v[32:33], v[110:111], v[2:3], v[32:33] op_sel_hi:[1,0,1]
	v_pk_fma_f32 v[30:31], v[108:109], v[2:3], v[30:31] op_sel_hi:[1,0,1]
	s_waitcnt lgkmcnt(0)
	v_mov_b32_e32 v2, v9
	v_pk_fma_f32 v[130:131], v[110:111], v[140:141], v[12:13] op_sel_hi:[1,0,1]
	v_pk_fma_f32 v[16:17], v[110:111], v[10:11], v[16:17] op_sel_hi:[1,0,1]
	v_pk_fma_f32 v[14:15], v[108:109], v[10:11], v[14:15] op_sel_hi:[1,0,1]
	v_pk_fma_f32 v[28:29], v[110:111], v[4:5], v[28:29] op_sel_hi:[1,0,1]
	v_pk_fma_f32 v[26:27], v[108:109], v[4:5], v[26:27] op_sel_hi:[1,0,1]
	v_pk_fma_f32 v[36:37], v[110:111], v[6:7], v[36:37] op_sel_hi:[1,0,1]
	v_pk_fma_f32 v[34:35], v[108:109], v[6:7], v[34:35] op_sel_hi:[1,0,1]
	v_pk_fma_f32 v[40:41], v[110:111], v[6:7], v[40:41] op_sel:[0,1,0]
	v_pk_fma_f32 v[38:39], v[108:109], v[6:7], v[38:39] op_sel:[0,1,0]
	v_pk_fma_f32 v[44:45], v[110:111], v[8:9], v[44:45] op_sel_hi:[1,0,1]
	v_pk_fma_f32 v[42:43], v[108:109], v[8:9], v[42:43] op_sel_hi:[1,0,1]
	v_pk_fma_f32 v[48:49], v[110:111], v[2:3], v[48:49] op_sel_hi:[1,0,1]
	v_pk_fma_f32 v[46:47], v[108:109], v[2:3], v[46:47] op_sel_hi:[1,0,1]
	ds_read_b128 v[2:5], v125 offset:96
	ds_read_b128 v[6:9], v125 offset:112
	ds_read_b128 v[10:13], v125 offset:128
	v_pk_fma_f32 v[112:113], v[110:111], v[138:139], v[142:143] op_sel_hi:[1,0,1]
	v_pk_fma_f32 v[114:115], v[108:109], v[138:139], v[144:145] op_sel_hi:[1,0,1]
	v_pk_fma_f32 v[128:129], v[110:111], v[138:139], v[146:147] op_sel:[0,1,0]
	v_pk_fma_f32 v[126:127], v[108:109], v[138:139], v[126:127] op_sel:[0,1,0]
	s_waitcnt vmcnt(13) lgkmcnt(2)
	v_pk_fma_f32 v[108:109], v[106:107], v[2:3], v[112:113] op_sel_hi:[1,0,1]
	v_pk_fma_f32 v[110:111], v[104:105], v[2:3], v[114:115] op_sel_hi:[1,0,1]
	v_pk_fma_f32 v[112:113], v[106:107], v[2:3], v[128:129] op_sel:[0,1,0]
	v_pk_fma_f32 v[114:115], v[104:105], v[2:3], v[126:127] op_sel:[0,1,0]
	v_mov_b32_e32 v2, v5
	v_pk_fma_f32 v[16:17], v[106:107], v[2:3], v[16:17] op_sel_hi:[1,0,1]
	v_pk_fma_f32 v[14:15], v[104:105], v[2:3], v[14:15] op_sel_hi:[1,0,1]
	s_waitcnt lgkmcnt(1)
	v_mov_b32_e32 v2, v9
	v_pk_fma_f32 v[32:33], v[106:107], v[2:3], v[32:33] op_sel_hi:[1,0,1]
	v_pk_fma_f32 v[30:31], v[104:105], v[2:3], v[30:31] op_sel_hi:[1,0,1]
	s_waitcnt lgkmcnt(0)
	v_mov_b32_e32 v2, v13
	v_pk_fma_f32 v[126:127], v[106:107], v[4:5], v[130:131] op_sel_hi:[1,0,1]
	v_pk_fma_f32 v[128:129], v[104:105], v[4:5], v[132:133] op_sel_hi:[1,0,1]
	v_pk_fma_f32 v[20:21], v[106:107], v[6:7], v[20:21] op_sel_hi:[1,0,1]
	v_pk_fma_f32 v[18:19], v[104:105], v[6:7], v[18:19] op_sel_hi:[1,0,1]
	v_pk_fma_f32 v[24:25], v[106:107], v[6:7], v[24:25] op_sel:[0,1,0]
	v_pk_fma_f32 v[22:23], v[104:105], v[6:7], v[22:23] op_sel:[0,1,0]
	v_pk_fma_f32 v[28:29], v[106:107], v[8:9], v[28:29] op_sel_hi:[1,0,1]
	v_pk_fma_f32 v[26:27], v[104:105], v[8:9], v[26:27] op_sel_hi:[1,0,1]
	v_pk_fma_f32 v[36:37], v[106:107], v[10:11], v[36:37] op_sel_hi:[1,0,1]
	v_pk_fma_f32 v[34:35], v[104:105], v[10:11], v[34:35] op_sel_hi:[1,0,1]
	v_pk_fma_f32 v[40:41], v[106:107], v[10:11], v[40:41] op_sel:[0,1,0]
	v_pk_fma_f32 v[38:39], v[104:105], v[10:11], v[38:39] op_sel:[0,1,0]
	v_pk_fma_f32 v[44:45], v[106:107], v[12:13], v[44:45] op_sel_hi:[1,0,1]
	v_pk_fma_f32 v[42:43], v[104:105], v[12:13], v[42:43] op_sel_hi:[1,0,1]
	v_pk_fma_f32 v[48:49], v[106:107], v[2:3], v[48:49] op_sel_hi:[1,0,1]
	v_pk_fma_f32 v[46:47], v[104:105], v[2:3], v[46:47] op_sel_hi:[1,0,1]
	ds_read_b128 v[2:5], v125 offset:144
	ds_read_b128 v[6:9], v125 offset:160
	ds_read_b128 v[10:13], v125 offset:176
	s_addc_u32 s11, s11, 0
	s_cmp_ge_i32 s16, s13
	s_waitcnt vmcnt(12) lgkmcnt(2)
	v_pk_fma_f32 v[104:105], v[102:103], v[2:3], v[108:109] op_sel_hi:[1,0,1]
	v_pk_fma_f32 v[106:107], v[100:101], v[2:3], v[110:111] op_sel_hi:[1,0,1]
	v_pk_fma_f32 v[108:109], v[102:103], v[2:3], v[112:113] op_sel:[0,1,0]
	v_pk_fma_f32 v[110:111], v[100:101], v[2:3], v[114:115] op_sel:[0,1,0]
	v_mov_b32_e32 v2, v5
	v_pk_fma_f32 v[16:17], v[102:103], v[2:3], v[16:17] op_sel_hi:[1,0,1]
	v_pk_fma_f32 v[14:15], v[100:101], v[2:3], v[14:15] op_sel_hi:[1,0,1]
	s_waitcnt lgkmcnt(1)
	v_mov_b32_e32 v2, v9
	v_pk_fma_f32 v[32:33], v[102:103], v[2:3], v[32:33] op_sel_hi:[1,0,1]
	v_pk_fma_f32 v[30:31], v[100:101], v[2:3], v[30:31] op_sel_hi:[1,0,1]
	s_waitcnt lgkmcnt(0)
	v_mov_b32_e32 v2, v13
	v_pk_fma_f32 v[112:113], v[102:103], v[4:5], v[126:127] op_sel_hi:[1,0,1]
	v_pk_fma_f32 v[114:115], v[100:101], v[4:5], v[128:129] op_sel_hi:[1,0,1]
	v_pk_fma_f32 v[20:21], v[102:103], v[6:7], v[20:21] op_sel_hi:[1,0,1]
	v_pk_fma_f32 v[18:19], v[100:101], v[6:7], v[18:19] op_sel_hi:[1,0,1]
	v_pk_fma_f32 v[24:25], v[102:103], v[6:7], v[24:25] op_sel:[0,1,0]
	v_pk_fma_f32 v[22:23], v[100:101], v[6:7], v[22:23] op_sel:[0,1,0]
	v_pk_fma_f32 v[28:29], v[102:103], v[8:9], v[28:29] op_sel_hi:[1,0,1]
	v_pk_fma_f32 v[26:27], v[100:101], v[8:9], v[26:27] op_sel_hi:[1,0,1]
	v_pk_fma_f32 v[36:37], v[102:103], v[10:11], v[36:37] op_sel_hi:[1,0,1]
	v_pk_fma_f32 v[34:35], v[100:101], v[10:11], v[34:35] op_sel_hi:[1,0,1]
	v_pk_fma_f32 v[40:41], v[102:103], v[10:11], v[40:41] op_sel:[0,1,0]
	v_pk_fma_f32 v[38:39], v[100:101], v[10:11], v[38:39] op_sel:[0,1,0]
	v_pk_fma_f32 v[44:45], v[102:103], v[12:13], v[44:45] op_sel_hi:[1,0,1]
	v_pk_fma_f32 v[42:43], v[100:101], v[12:13], v[42:43] op_sel_hi:[1,0,1]
	v_pk_fma_f32 v[48:49], v[102:103], v[2:3], v[48:49] op_sel_hi:[1,0,1]
	v_pk_fma_f32 v[46:47], v[100:101], v[2:3], v[46:47] op_sel_hi:[1,0,1]
	ds_read_b128 v[2:5], v125 offset:192
	ds_read_b128 v[6:9], v125 offset:208
	ds_read_b128 v[10:13], v125 offset:224
	s_waitcnt vmcnt(11) lgkmcnt(2)
	v_pk_fma_f32 v[100:101], v[98:99], v[2:3], v[104:105] op_sel_hi:[1,0,1]
	v_pk_fma_f32 v[102:103], v[96:97], v[2:3], v[106:107] op_sel_hi:[1,0,1]
	v_pk_fma_f32 v[104:105], v[98:99], v[2:3], v[108:109] op_sel:[0,1,0]
	v_pk_fma_f32 v[106:107], v[96:97], v[2:3], v[110:111] op_sel:[0,1,0]
	v_mov_b32_e32 v2, v5
	v_pk_fma_f32 v[16:17], v[98:99], v[2:3], v[16:17] op_sel_hi:[1,0,1]
	v_pk_fma_f32 v[14:15], v[96:97], v[2:3], v[14:15] op_sel_hi:[1,0,1]
	s_waitcnt lgkmcnt(1)
	v_mov_b32_e32 v2, v9
	v_pk_fma_f32 v[32:33], v[98:99], v[2:3], v[32:33] op_sel_hi:[1,0,1]
	v_pk_fma_f32 v[30:31], v[96:97], v[2:3], v[30:31] op_sel_hi:[1,0,1]
	s_waitcnt lgkmcnt(0)
	v_mov_b32_e32 v2, v13
	v_pk_fma_f32 v[108:109], v[98:99], v[4:5], v[112:113] op_sel_hi:[1,0,1]
	v_pk_fma_f32 v[110:111], v[96:97], v[4:5], v[114:115] op_sel_hi:[1,0,1]
	v_pk_fma_f32 v[20:21], v[98:99], v[6:7], v[20:21] op_sel_hi:[1,0,1]
	v_pk_fma_f32 v[18:19], v[96:97], v[6:7], v[18:19] op_sel_hi:[1,0,1]
	v_pk_fma_f32 v[24:25], v[98:99], v[6:7], v[24:25] op_sel:[0,1,0]
	v_pk_fma_f32 v[22:23], v[96:97], v[6:7], v[22:23] op_sel:[0,1,0]
	v_pk_fma_f32 v[28:29], v[98:99], v[8:9], v[28:29] op_sel_hi:[1,0,1]
	v_pk_fma_f32 v[26:27], v[96:97], v[8:9], v[26:27] op_sel_hi:[1,0,1]
	v_pk_fma_f32 v[36:37], v[98:99], v[10:11], v[36:37] op_sel_hi:[1,0,1]
	v_pk_fma_f32 v[34:35], v[96:97], v[10:11], v[34:35] op_sel_hi:[1,0,1]
	v_pk_fma_f32 v[40:41], v[98:99], v[10:11], v[40:41] op_sel:[0,1,0]
	v_pk_fma_f32 v[38:39], v[96:97], v[10:11], v[38:39] op_sel:[0,1,0]
	v_pk_fma_f32 v[44:45], v[98:99], v[12:13], v[44:45] op_sel_hi:[1,0,1]
	v_pk_fma_f32 v[42:43], v[96:97], v[12:13], v[42:43] op_sel_hi:[1,0,1]
	v_pk_fma_f32 v[48:49], v[98:99], v[2:3], v[48:49] op_sel_hi:[1,0,1]
	v_pk_fma_f32 v[46:47], v[96:97], v[2:3], v[46:47] op_sel_hi:[1,0,1]
	ds_read_b128 v[2:5], v125 offset:240
	ds_read_b128 v[6:9], v125 offset:256
	ds_read_b128 v[10:13], v125 offset:272
	s_waitcnt vmcnt(10) lgkmcnt(2)
	v_pk_fma_f32 v[96:97], v[94:95], v[2:3], v[100:101] op_sel_hi:[1,0,1]
	v_pk_fma_f32 v[98:99], v[92:93], v[2:3], v[102:103] op_sel_hi:[1,0,1]
	v_pk_fma_f32 v[100:101], v[94:95], v[2:3], v[104:105] op_sel:[0,1,0]
	v_pk_fma_f32 v[102:103], v[92:93], v[2:3], v[106:107] op_sel:[0,1,0]
	v_mov_b32_e32 v2, v5
	v_pk_fma_f32 v[16:17], v[94:95], v[2:3], v[16:17] op_sel_hi:[1,0,1]
	v_pk_fma_f32 v[14:15], v[92:93], v[2:3], v[14:15] op_sel_hi:[1,0,1]
	s_waitcnt lgkmcnt(1)
	v_mov_b32_e32 v2, v9
	v_pk_fma_f32 v[32:33], v[94:95], v[2:3], v[32:33] op_sel_hi:[1,0,1]
	v_pk_fma_f32 v[30:31], v[92:93], v[2:3], v[30:31] op_sel_hi:[1,0,1]
	s_waitcnt lgkmcnt(0)
	v_mov_b32_e32 v2, v13
	v_pk_fma_f32 v[104:105], v[94:95], v[4:5], v[108:109] op_sel_hi:[1,0,1]
	v_pk_fma_f32 v[106:107], v[92:93], v[4:5], v[110:111] op_sel_hi:[1,0,1]
	v_pk_fma_f32 v[20:21], v[94:95], v[6:7], v[20:21] op_sel_hi:[1,0,1]
	v_pk_fma_f32 v[18:19], v[92:93], v[6:7], v[18:19] op_sel_hi:[1,0,1]
	v_pk_fma_f32 v[24:25], v[94:95], v[6:7], v[24:25] op_sel:[0,1,0]
	v_pk_fma_f32 v[22:23], v[92:93], v[6:7], v[22:23] op_sel:[0,1,0]
	v_pk_fma_f32 v[28:29], v[94:95], v[8:9], v[28:29] op_sel_hi:[1,0,1]
	v_pk_fma_f32 v[26:27], v[92:93], v[8:9], v[26:27] op_sel_hi:[1,0,1]
	v_pk_fma_f32 v[36:37], v[94:95], v[10:11], v[36:37] op_sel_hi:[1,0,1]
	v_pk_fma_f32 v[34:35], v[92:93], v[10:11], v[34:35] op_sel_hi:[1,0,1]
	v_pk_fma_f32 v[40:41], v[94:95], v[10:11], v[40:41] op_sel:[0,1,0]
	v_pk_fma_f32 v[38:39], v[92:93], v[10:11], v[38:39] op_sel:[0,1,0]
	v_pk_fma_f32 v[44:45], v[94:95], v[12:13], v[44:45] op_sel_hi:[1,0,1]
	v_pk_fma_f32 v[42:43], v[92:93], v[12:13], v[42:43] op_sel_hi:[1,0,1]
	v_pk_fma_f32 v[48:49], v[94:95], v[2:3], v[48:49] op_sel_hi:[1,0,1]
	v_pk_fma_f32 v[46:47], v[92:93], v[2:3], v[46:47] op_sel_hi:[1,0,1]
	ds_read_b128 v[2:5], v125 offset:288
	ds_read_b128 v[6:9], v125 offset:304
	ds_read_b128 v[10:13], v125 offset:320
	s_waitcnt vmcnt(9) lgkmcnt(2)
	v_pk_fma_f32 v[92:93], v[90:91], v[2:3], v[96:97] op_sel_hi:[1,0,1]
	v_pk_fma_f32 v[94:95], v[88:89], v[2:3], v[98:99] op_sel_hi:[1,0,1]
	v_pk_fma_f32 v[96:97], v[90:91], v[2:3], v[100:101] op_sel:[0,1,0]
	v_pk_fma_f32 v[98:99], v[88:89], v[2:3], v[102:103] op_sel:[0,1,0]
	v_mov_b32_e32 v2, v5
	v_pk_fma_f32 v[16:17], v[90:91], v[2:3], v[16:17] op_sel_hi:[1,0,1]
	v_pk_fma_f32 v[14:15], v[88:89], v[2:3], v[14:15] op_sel_hi:[1,0,1]
	s_waitcnt lgkmcnt(1)
	v_mov_b32_e32 v2, v9
	v_pk_fma_f32 v[32:33], v[90:91], v[2:3], v[32:33] op_sel_hi:[1,0,1]
	v_pk_fma_f32 v[30:31], v[88:89], v[2:3], v[30:31] op_sel_hi:[1,0,1]
	s_waitcnt lgkmcnt(0)
	v_mov_b32_e32 v2, v13
	v_pk_fma_f32 v[100:101], v[90:91], v[4:5], v[104:105] op_sel_hi:[1,0,1]
	v_pk_fma_f32 v[102:103], v[88:89], v[4:5], v[106:107] op_sel_hi:[1,0,1]
	v_pk_fma_f32 v[20:21], v[90:91], v[6:7], v[20:21] op_sel_hi:[1,0,1]
	v_pk_fma_f32 v[18:19], v[88:89], v[6:7], v[18:19] op_sel_hi:[1,0,1]
	v_pk_fma_f32 v[24:25], v[90:91], v[6:7], v[24:25] op_sel:[0,1,0]
	v_pk_fma_f32 v[22:23], v[88:89], v[6:7], v[22:23] op_sel:[0,1,0]
	v_pk_fma_f32 v[28:29], v[90:91], v[8:9], v[28:29] op_sel_hi:[1,0,1]
	v_pk_fma_f32 v[26:27], v[88:89], v[8:9], v[26:27] op_sel_hi:[1,0,1]
	v_pk_fma_f32 v[36:37], v[90:91], v[10:11], v[36:37] op_sel_hi:[1,0,1]
	v_pk_fma_f32 v[34:35], v[88:89], v[10:11], v[34:35] op_sel_hi:[1,0,1]
	v_pk_fma_f32 v[40:41], v[90:91], v[10:11], v[40:41] op_sel:[0,1,0]
	v_pk_fma_f32 v[38:39], v[88:89], v[10:11], v[38:39] op_sel:[0,1,0]
	v_pk_fma_f32 v[44:45], v[90:91], v[12:13], v[44:45] op_sel_hi:[1,0,1]
	v_pk_fma_f32 v[42:43], v[88:89], v[12:13], v[42:43] op_sel_hi:[1,0,1]
	v_pk_fma_f32 v[48:49], v[90:91], v[2:3], v[48:49] op_sel_hi:[1,0,1]
	v_pk_fma_f32 v[46:47], v[88:89], v[2:3], v[46:47] op_sel_hi:[1,0,1]
	ds_read_b128 v[2:5], v125 offset:336
	ds_read_b128 v[6:9], v125 offset:352
	ds_read_b128 v[10:13], v125 offset:368
	s_waitcnt vmcnt(8) lgkmcnt(2)
	v_pk_fma_f32 v[88:89], v[86:87], v[2:3], v[92:93] op_sel_hi:[1,0,1]
	v_pk_fma_f32 v[90:91], v[84:85], v[2:3], v[94:95] op_sel_hi:[1,0,1]
	v_pk_fma_f32 v[92:93], v[86:87], v[2:3], v[96:97] op_sel:[0,1,0]
	v_pk_fma_f32 v[94:95], v[84:85], v[2:3], v[98:99] op_sel:[0,1,0]
	v_mov_b32_e32 v2, v5
	v_pk_fma_f32 v[16:17], v[86:87], v[2:3], v[16:17] op_sel_hi:[1,0,1]
	v_pk_fma_f32 v[14:15], v[84:85], v[2:3], v[14:15] op_sel_hi:[1,0,1]
	s_waitcnt lgkmcnt(1)
	v_mov_b32_e32 v2, v9
	v_pk_fma_f32 v[32:33], v[86:87], v[2:3], v[32:33] op_sel_hi:[1,0,1]
	v_pk_fma_f32 v[30:31], v[84:85], v[2:3], v[30:31] op_sel_hi:[1,0,1]
	s_waitcnt lgkmcnt(0)
	v_mov_b32_e32 v2, v13
	v_pk_fma_f32 v[96:97], v[86:87], v[4:5], v[100:101] op_sel_hi:[1,0,1]
	v_pk_fma_f32 v[98:99], v[84:85], v[4:5], v[102:103] op_sel_hi:[1,0,1]
	v_pk_fma_f32 v[20:21], v[86:87], v[6:7], v[20:21] op_sel_hi:[1,0,1]
	v_pk_fma_f32 v[18:19], v[84:85], v[6:7], v[18:19] op_sel_hi:[1,0,1]
	v_pk_fma_f32 v[24:25], v[86:87], v[6:7], v[24:25] op_sel:[0,1,0]
	v_pk_fma_f32 v[22:23], v[84:85], v[6:7], v[22:23] op_sel:[0,1,0]
	v_pk_fma_f32 v[28:29], v[86:87], v[8:9], v[28:29] op_sel_hi:[1,0,1]
	v_pk_fma_f32 v[26:27], v[84:85], v[8:9], v[26:27] op_sel_hi:[1,0,1]
	v_pk_fma_f32 v[36:37], v[86:87], v[10:11], v[36:37] op_sel_hi:[1,0,1]
	v_pk_fma_f32 v[34:35], v[84:85], v[10:11], v[34:35] op_sel_hi:[1,0,1]
	v_pk_fma_f32 v[40:41], v[86:87], v[10:11], v[40:41] op_sel:[0,1,0]
	v_pk_fma_f32 v[38:39], v[84:85], v[10:11], v[38:39] op_sel:[0,1,0]
	v_pk_fma_f32 v[44:45], v[86:87], v[12:13], v[44:45] op_sel_hi:[1,0,1]
	v_pk_fma_f32 v[42:43], v[84:85], v[12:13], v[42:43] op_sel_hi:[1,0,1]
	v_pk_fma_f32 v[48:49], v[86:87], v[2:3], v[48:49] op_sel_hi:[1,0,1]
	v_pk_fma_f32 v[46:47], v[84:85], v[2:3], v[46:47] op_sel_hi:[1,0,1]
	ds_read_b128 v[2:5], v125 offset:384
	ds_read_b128 v[6:9], v125 offset:400
	ds_read_b128 v[10:13], v125 offset:416
	s_waitcnt vmcnt(7) lgkmcnt(2)
	v_pk_fma_f32 v[84:85], v[78:79], v[2:3], v[88:89] op_sel_hi:[1,0,1]
	v_pk_fma_f32 v[86:87], v[76:77], v[2:3], v[90:91] op_sel_hi:[1,0,1]
	v_pk_fma_f32 v[88:89], v[78:79], v[2:3], v[92:93] op_sel:[0,1,0]
	v_pk_fma_f32 v[90:91], v[76:77], v[2:3], v[94:95] op_sel:[0,1,0]
	v_mov_b32_e32 v2, v5
	v_pk_fma_f32 v[16:17], v[78:79], v[2:3], v[16:17] op_sel_hi:[1,0,1]
	v_pk_fma_f32 v[14:15], v[76:77], v[2:3], v[14:15] op_sel_hi:[1,0,1]
	s_waitcnt lgkmcnt(1)
	v_mov_b32_e32 v2, v9
	v_pk_fma_f32 v[32:33], v[78:79], v[2:3], v[32:33] op_sel_hi:[1,0,1]
	v_pk_fma_f32 v[30:31], v[76:77], v[2:3], v[30:31] op_sel_hi:[1,0,1]
	s_waitcnt lgkmcnt(0)
	v_mov_b32_e32 v2, v13
	v_pk_fma_f32 v[92:93], v[78:79], v[4:5], v[96:97] op_sel_hi:[1,0,1]
	v_pk_fma_f32 v[94:95], v[76:77], v[4:5], v[98:99] op_sel_hi:[1,0,1]
	v_pk_fma_f32 v[20:21], v[78:79], v[6:7], v[20:21] op_sel_hi:[1,0,1]
	v_pk_fma_f32 v[18:19], v[76:77], v[6:7], v[18:19] op_sel_hi:[1,0,1]
	v_pk_fma_f32 v[24:25], v[78:79], v[6:7], v[24:25] op_sel:[0,1,0]
	v_pk_fma_f32 v[22:23], v[76:77], v[6:7], v[22:23] op_sel:[0,1,0]
	v_pk_fma_f32 v[28:29], v[78:79], v[8:9], v[28:29] op_sel_hi:[1,0,1]
	v_pk_fma_f32 v[26:27], v[76:77], v[8:9], v[26:27] op_sel_hi:[1,0,1]
	v_pk_fma_f32 v[36:37], v[78:79], v[10:11], v[36:37] op_sel_hi:[1,0,1]
	v_pk_fma_f32 v[34:35], v[76:77], v[10:11], v[34:35] op_sel_hi:[1,0,1]
	v_pk_fma_f32 v[40:41], v[78:79], v[10:11], v[40:41] op_sel:[0,1,0]
	v_pk_fma_f32 v[38:39], v[76:77], v[10:11], v[38:39] op_sel:[0,1,0]
	v_pk_fma_f32 v[44:45], v[78:79], v[12:13], v[44:45] op_sel_hi:[1,0,1]
	v_pk_fma_f32 v[42:43], v[76:77], v[12:13], v[42:43] op_sel_hi:[1,0,1]
	v_pk_fma_f32 v[48:49], v[78:79], v[2:3], v[48:49] op_sel_hi:[1,0,1]
	v_pk_fma_f32 v[46:47], v[76:77], v[2:3], v[46:47] op_sel_hi:[1,0,1]
	ds_read_b128 v[2:5], v125 offset:432
	ds_read_b128 v[6:9], v125 offset:448
	ds_read_b128 v[10:13], v125 offset:464
	s_waitcnt vmcnt(6) lgkmcnt(2)
	v_pk_fma_f32 v[76:77], v[74:75], v[2:3], v[84:85] op_sel_hi:[1,0,1]
	v_pk_fma_f32 v[78:79], v[72:73], v[2:3], v[86:87] op_sel_hi:[1,0,1]
	v_pk_fma_f32 v[84:85], v[74:75], v[2:3], v[88:89] op_sel:[0,1,0]
	v_pk_fma_f32 v[86:87], v[72:73], v[2:3], v[90:91] op_sel:[0,1,0]
	v_mov_b32_e32 v2, v5
	v_pk_fma_f32 v[16:17], v[74:75], v[2:3], v[16:17] op_sel_hi:[1,0,1]
	v_pk_fma_f32 v[14:15], v[72:73], v[2:3], v[14:15] op_sel_hi:[1,0,1]
	s_waitcnt lgkmcnt(1)
	v_mov_b32_e32 v2, v9
	v_pk_fma_f32 v[32:33], v[74:75], v[2:3], v[32:33] op_sel_hi:[1,0,1]
	v_pk_fma_f32 v[30:31], v[72:73], v[2:3], v[30:31] op_sel_hi:[1,0,1]
	s_waitcnt lgkmcnt(0)
	v_mov_b32_e32 v2, v13
	v_pk_fma_f32 v[88:89], v[74:75], v[4:5], v[92:93] op_sel_hi:[1,0,1]
	v_pk_fma_f32 v[90:91], v[72:73], v[4:5], v[94:95] op_sel_hi:[1,0,1]
	v_pk_fma_f32 v[20:21], v[74:75], v[6:7], v[20:21] op_sel_hi:[1,0,1]
	v_pk_fma_f32 v[18:19], v[72:73], v[6:7], v[18:19] op_sel_hi:[1,0,1]
	v_pk_fma_f32 v[24:25], v[74:75], v[6:7], v[24:25] op_sel:[0,1,0]
	v_pk_fma_f32 v[22:23], v[72:73], v[6:7], v[22:23] op_sel:[0,1,0]
	v_pk_fma_f32 v[28:29], v[74:75], v[8:9], v[28:29] op_sel_hi:[1,0,1]
	v_pk_fma_f32 v[26:27], v[72:73], v[8:9], v[26:27] op_sel_hi:[1,0,1]
	v_pk_fma_f32 v[36:37], v[74:75], v[10:11], v[36:37] op_sel_hi:[1,0,1]
	v_pk_fma_f32 v[34:35], v[72:73], v[10:11], v[34:35] op_sel_hi:[1,0,1]
	v_pk_fma_f32 v[40:41], v[74:75], v[10:11], v[40:41] op_sel:[0,1,0]
	v_pk_fma_f32 v[38:39], v[72:73], v[10:11], v[38:39] op_sel:[0,1,0]
	v_pk_fma_f32 v[44:45], v[74:75], v[12:13], v[44:45] op_sel_hi:[1,0,1]
	v_pk_fma_f32 v[42:43], v[72:73], v[12:13], v[42:43] op_sel_hi:[1,0,1]
	v_pk_fma_f32 v[48:49], v[74:75], v[2:3], v[48:49] op_sel_hi:[1,0,1]
	v_pk_fma_f32 v[46:47], v[72:73], v[2:3], v[46:47] op_sel_hi:[1,0,1]
	ds_read_b128 v[2:5], v125 offset:480
	ds_read_b128 v[6:9], v125 offset:496
	ds_read_b128 v[10:13], v125 offset:512
	s_waitcnt vmcnt(5) lgkmcnt(2)
	v_pk_fma_f32 v[72:73], v[70:71], v[2:3], v[76:77] op_sel_hi:[1,0,1]
	v_pk_fma_f32 v[74:75], v[68:69], v[2:3], v[78:79] op_sel_hi:[1,0,1]
	v_pk_fma_f32 v[76:77], v[70:71], v[2:3], v[84:85] op_sel:[0,1,0]
	v_pk_fma_f32 v[78:79], v[68:69], v[2:3], v[86:87] op_sel:[0,1,0]
	v_mov_b32_e32 v2, v5
	v_pk_fma_f32 v[16:17], v[70:71], v[2:3], v[16:17] op_sel_hi:[1,0,1]
	v_pk_fma_f32 v[14:15], v[68:69], v[2:3], v[14:15] op_sel_hi:[1,0,1]
	s_waitcnt lgkmcnt(1)
	v_mov_b32_e32 v2, v9
	v_pk_fma_f32 v[32:33], v[70:71], v[2:3], v[32:33] op_sel_hi:[1,0,1]
	v_pk_fma_f32 v[30:31], v[68:69], v[2:3], v[30:31] op_sel_hi:[1,0,1]
	s_waitcnt lgkmcnt(0)
	v_mov_b32_e32 v2, v13
	v_pk_fma_f32 v[84:85], v[70:71], v[4:5], v[88:89] op_sel_hi:[1,0,1]
	v_pk_fma_f32 v[86:87], v[68:69], v[4:5], v[90:91] op_sel_hi:[1,0,1]
	v_pk_fma_f32 v[20:21], v[70:71], v[6:7], v[20:21] op_sel_hi:[1,0,1]
	v_pk_fma_f32 v[18:19], v[68:69], v[6:7], v[18:19] op_sel_hi:[1,0,1]
	v_pk_fma_f32 v[24:25], v[70:71], v[6:7], v[24:25] op_sel:[0,1,0]
	v_pk_fma_f32 v[22:23], v[68:69], v[6:7], v[22:23] op_sel:[0,1,0]
	v_pk_fma_f32 v[28:29], v[70:71], v[8:9], v[28:29] op_sel_hi:[1,0,1]
	v_pk_fma_f32 v[26:27], v[68:69], v[8:9], v[26:27] op_sel_hi:[1,0,1]
	v_pk_fma_f32 v[36:37], v[70:71], v[10:11], v[36:37] op_sel_hi:[1,0,1]
	v_pk_fma_f32 v[34:35], v[68:69], v[10:11], v[34:35] op_sel_hi:[1,0,1]
	v_pk_fma_f32 v[40:41], v[70:71], v[10:11], v[40:41] op_sel:[0,1,0]
	v_pk_fma_f32 v[38:39], v[68:69], v[10:11], v[38:39] op_sel:[0,1,0]
	v_pk_fma_f32 v[44:45], v[70:71], v[12:13], v[44:45] op_sel_hi:[1,0,1]
	v_pk_fma_f32 v[42:43], v[68:69], v[12:13], v[42:43] op_sel_hi:[1,0,1]
	v_pk_fma_f32 v[48:49], v[70:71], v[2:3], v[48:49] op_sel_hi:[1,0,1]
	v_pk_fma_f32 v[46:47], v[68:69], v[2:3], v[46:47] op_sel_hi:[1,0,1]
	ds_read_b128 v[2:5], v125 offset:528
	ds_read_b128 v[6:9], v125 offset:544
	ds_read_b128 v[10:13], v125 offset:560
	s_waitcnt vmcnt(4) lgkmcnt(2)
	v_pk_fma_f32 v[68:69], v[64:65], v[2:3], v[72:73] op_sel_hi:[1,0,1]
	v_pk_fma_f32 v[70:71], v[62:63], v[2:3], v[74:75] op_sel_hi:[1,0,1]
	v_pk_fma_f32 v[72:73], v[64:65], v[2:3], v[76:77] op_sel:[0,1,0]
	v_pk_fma_f32 v[74:75], v[62:63], v[2:3], v[78:79] op_sel:[0,1,0]
	v_mov_b32_e32 v2, v5
	v_pk_fma_f32 v[16:17], v[64:65], v[2:3], v[16:17] op_sel_hi:[1,0,1]
	v_pk_fma_f32 v[14:15], v[62:63], v[2:3], v[14:15] op_sel_hi:[1,0,1]
	s_waitcnt lgkmcnt(1)
	v_mov_b32_e32 v2, v9
	v_pk_fma_f32 v[32:33], v[64:65], v[2:3], v[32:33] op_sel_hi:[1,0,1]
	v_pk_fma_f32 v[30:31], v[62:63], v[2:3], v[30:31] op_sel_hi:[1,0,1]
	s_waitcnt lgkmcnt(0)
	v_mov_b32_e32 v2, v13
	v_pk_fma_f32 v[76:77], v[64:65], v[4:5], v[84:85] op_sel_hi:[1,0,1]
	v_pk_fma_f32 v[78:79], v[62:63], v[4:5], v[86:87] op_sel_hi:[1,0,1]
	v_pk_fma_f32 v[20:21], v[64:65], v[6:7], v[20:21] op_sel_hi:[1,0,1]
	v_pk_fma_f32 v[18:19], v[62:63], v[6:7], v[18:19] op_sel_hi:[1,0,1]
	v_pk_fma_f32 v[24:25], v[64:65], v[6:7], v[24:25] op_sel:[0,1,0]
	v_pk_fma_f32 v[22:23], v[62:63], v[6:7], v[22:23] op_sel:[0,1,0]
	v_pk_fma_f32 v[28:29], v[64:65], v[8:9], v[28:29] op_sel_hi:[1,0,1]
	v_pk_fma_f32 v[26:27], v[62:63], v[8:9], v[26:27] op_sel_hi:[1,0,1]
	v_pk_fma_f32 v[36:37], v[64:65], v[10:11], v[36:37] op_sel_hi:[1,0,1]
	v_pk_fma_f32 v[34:35], v[62:63], v[10:11], v[34:35] op_sel_hi:[1,0,1]
	v_pk_fma_f32 v[40:41], v[64:65], v[10:11], v[40:41] op_sel:[0,1,0]
	v_pk_fma_f32 v[38:39], v[62:63], v[10:11], v[38:39] op_sel:[0,1,0]
	v_pk_fma_f32 v[44:45], v[64:65], v[12:13], v[44:45] op_sel_hi:[1,0,1]
	v_pk_fma_f32 v[42:43], v[62:63], v[12:13], v[42:43] op_sel_hi:[1,0,1]
	v_pk_fma_f32 v[48:49], v[64:65], v[2:3], v[48:49] op_sel_hi:[1,0,1]
	v_pk_fma_f32 v[46:47], v[62:63], v[2:3], v[46:47] op_sel_hi:[1,0,1]
	ds_read_b128 v[2:5], v125 offset:576
	ds_read_b128 v[6:9], v125 offset:592
	ds_read_b128 v[10:13], v125 offset:608
	s_waitcnt vmcnt(3) lgkmcnt(2)
	v_pk_fma_f32 v[62:63], v[60:61], v[2:3], v[68:69] op_sel_hi:[1,0,1]
	v_pk_fma_f32 v[64:65], v[58:59], v[2:3], v[70:71] op_sel_hi:[1,0,1]
	v_pk_fma_f32 v[68:69], v[60:61], v[2:3], v[72:73] op_sel:[0,1,0]
	v_pk_fma_f32 v[70:71], v[58:59], v[2:3], v[74:75] op_sel:[0,1,0]
	v_mov_b32_e32 v2, v5
	v_pk_fma_f32 v[16:17], v[60:61], v[2:3], v[16:17] op_sel_hi:[1,0,1]
	v_pk_fma_f32 v[14:15], v[58:59], v[2:3], v[14:15] op_sel_hi:[1,0,1]
	s_waitcnt lgkmcnt(1)
	v_mov_b32_e32 v2, v9
	v_pk_fma_f32 v[32:33], v[60:61], v[2:3], v[32:33] op_sel_hi:[1,0,1]
	v_pk_fma_f32 v[30:31], v[58:59], v[2:3], v[30:31] op_sel_hi:[1,0,1]
	s_waitcnt lgkmcnt(0)
	v_mov_b32_e32 v2, v13
	v_pk_fma_f32 v[72:73], v[60:61], v[4:5], v[76:77] op_sel_hi:[1,0,1]
	v_pk_fma_f32 v[74:75], v[58:59], v[4:5], v[78:79] op_sel_hi:[1,0,1]
	v_pk_fma_f32 v[20:21], v[60:61], v[6:7], v[20:21] op_sel_hi:[1,0,1]
	v_pk_fma_f32 v[18:19], v[58:59], v[6:7], v[18:19] op_sel_hi:[1,0,1]
	v_pk_fma_f32 v[24:25], v[60:61], v[6:7], v[24:25] op_sel:[0,1,0]
	v_pk_fma_f32 v[22:23], v[58:59], v[6:7], v[22:23] op_sel:[0,1,0]
	v_pk_fma_f32 v[28:29], v[60:61], v[8:9], v[28:29] op_sel_hi:[1,0,1]
	v_pk_fma_f32 v[26:27], v[58:59], v[8:9], v[26:27] op_sel_hi:[1,0,1]
	v_pk_fma_f32 v[36:37], v[60:61], v[10:11], v[36:37] op_sel_hi:[1,0,1]
	v_pk_fma_f32 v[34:35], v[58:59], v[10:11], v[34:35] op_sel_hi:[1,0,1]
	v_pk_fma_f32 v[40:41], v[60:61], v[10:11], v[40:41] op_sel:[0,1,0]
	v_pk_fma_f32 v[38:39], v[58:59], v[10:11], v[38:39] op_sel:[0,1,0]
	v_pk_fma_f32 v[44:45], v[60:61], v[12:13], v[44:45] op_sel_hi:[1,0,1]
	v_pk_fma_f32 v[42:43], v[58:59], v[12:13], v[42:43] op_sel_hi:[1,0,1]
	v_pk_fma_f32 v[48:49], v[60:61], v[2:3], v[48:49] op_sel_hi:[1,0,1]
	v_pk_fma_f32 v[46:47], v[58:59], v[2:3], v[46:47] op_sel_hi:[1,0,1]
	ds_read_b128 v[2:5], v125 offset:624
	ds_read_b128 v[6:9], v125 offset:640
	ds_read_b128 v[10:13], v125 offset:656
	s_waitcnt vmcnt(2) lgkmcnt(2)
	v_pk_fma_f32 v[58:59], v[56:57], v[2:3], v[62:63] op_sel_hi:[1,0,1]
	v_pk_fma_f32 v[60:61], v[54:55], v[2:3], v[64:65] op_sel_hi:[1,0,1]
	v_pk_fma_f32 v[62:63], v[56:57], v[2:3], v[68:69] op_sel:[0,1,0]
	v_pk_fma_f32 v[64:65], v[54:55], v[2:3], v[70:71] op_sel:[0,1,0]
	v_mov_b32_e32 v2, v5
	v_pk_fma_f32 v[16:17], v[56:57], v[2:3], v[16:17] op_sel_hi:[1,0,1]
	v_pk_fma_f32 v[14:15], v[54:55], v[2:3], v[14:15] op_sel_hi:[1,0,1]
	s_waitcnt lgkmcnt(1)
	v_mov_b32_e32 v2, v9
	v_pk_fma_f32 v[32:33], v[56:57], v[2:3], v[32:33] op_sel_hi:[1,0,1]
	v_pk_fma_f32 v[30:31], v[54:55], v[2:3], v[30:31] op_sel_hi:[1,0,1]
	s_waitcnt lgkmcnt(0)
	v_mov_b32_e32 v2, v13
	v_pk_fma_f32 v[68:69], v[56:57], v[4:5], v[72:73] op_sel_hi:[1,0,1]
	v_pk_fma_f32 v[70:71], v[54:55], v[4:5], v[74:75] op_sel_hi:[1,0,1]
	v_pk_fma_f32 v[20:21], v[56:57], v[6:7], v[20:21] op_sel_hi:[1,0,1]
	v_pk_fma_f32 v[18:19], v[54:55], v[6:7], v[18:19] op_sel_hi:[1,0,1]
	v_pk_fma_f32 v[24:25], v[56:57], v[6:7], v[24:25] op_sel:[0,1,0]
	v_pk_fma_f32 v[22:23], v[54:55], v[6:7], v[22:23] op_sel:[0,1,0]
	v_pk_fma_f32 v[28:29], v[56:57], v[8:9], v[28:29] op_sel_hi:[1,0,1]
	v_pk_fma_f32 v[26:27], v[54:55], v[8:9], v[26:27] op_sel_hi:[1,0,1]
	v_pk_fma_f32 v[36:37], v[56:57], v[10:11], v[36:37] op_sel_hi:[1,0,1]
	v_pk_fma_f32 v[34:35], v[54:55], v[10:11], v[34:35] op_sel_hi:[1,0,1]
	v_pk_fma_f32 v[40:41], v[56:57], v[10:11], v[40:41] op_sel:[0,1,0]
	v_pk_fma_f32 v[38:39], v[54:55], v[10:11], v[38:39] op_sel:[0,1,0]
	v_pk_fma_f32 v[44:45], v[56:57], v[12:13], v[44:45] op_sel_hi:[1,0,1]
	v_pk_fma_f32 v[42:43], v[54:55], v[12:13], v[42:43] op_sel_hi:[1,0,1]
	v_pk_fma_f32 v[48:49], v[56:57], v[2:3], v[48:49] op_sel_hi:[1,0,1]
	v_pk_fma_f32 v[46:47], v[54:55], v[2:3], v[46:47] op_sel_hi:[1,0,1]
	ds_read_b128 v[2:5], v125 offset:672
	ds_read_b128 v[6:9], v125 offset:688
	ds_read_b128 v[10:13], v125 offset:704
	s_waitcnt vmcnt(1) lgkmcnt(2)
	v_pk_fma_f32 v[54:55], v[52:53], v[2:3], v[58:59] op_sel_hi:[1,0,1]
	v_pk_fma_f32 v[56:57], v[50:51], v[2:3], v[60:61] op_sel_hi:[1,0,1]
	v_pk_fma_f32 v[58:59], v[52:53], v[2:3], v[62:63] op_sel:[0,1,0]
	v_pk_fma_f32 v[60:61], v[50:51], v[2:3], v[64:65] op_sel:[0,1,0]
	v_mov_b32_e32 v2, v5
	v_pk_fma_f32 v[62:63], v[52:53], v[4:5], v[68:69] op_sel_hi:[1,0,1]
	v_pk_fma_f32 v[16:17], v[52:53], v[2:3], v[16:17] op_sel_hi:[1,0,1]
	v_pk_fma_f32 v[68:69], v[50:51], v[2:3], v[14:15] op_sel_hi:[1,0,1]
	s_waitcnt lgkmcnt(1)
	v_mov_b32_e32 v2, v9
	v_pk_fma_f32 v[32:33], v[52:53], v[2:3], v[32:33] op_sel_hi:[1,0,1]
	v_pk_fma_f32 v[72:73], v[50:51], v[2:3], v[30:31] op_sel_hi:[1,0,1]
	s_waitcnt lgkmcnt(0)
	v_mov_b32_e32 v2, v13
	v_pk_fma_f32 v[64:65], v[50:51], v[4:5], v[70:71] op_sel_hi:[1,0,1]
	v_pk_fma_f32 v[18:19], v[50:51], v[6:7], v[18:19] op_sel_hi:[1,0,1]
	v_pk_fma_f32 v[22:23], v[50:51], v[6:7], v[22:23] op_sel:[0,1,0]
	v_pk_fma_f32 v[70:71], v[52:53], v[8:9], v[28:29] op_sel_hi:[1,0,1]
	v_pk_fma_f32 v[26:27], v[50:51], v[8:9], v[26:27] op_sel_hi:[1,0,1]
	v_pk_fma_f32 v[34:35], v[50:51], v[10:11], v[34:35] op_sel_hi:[1,0,1]
	v_pk_fma_f32 v[38:39], v[50:51], v[10:11], v[38:39] op_sel:[0,1,0]
	v_pk_fma_f32 v[74:75], v[52:53], v[12:13], v[44:45] op_sel_hi:[1,0,1]
	v_pk_fma_f32 v[42:43], v[50:51], v[12:13], v[42:43] op_sel_hi:[1,0,1]
	v_pk_fma_f32 v[50:51], v[50:51], v[2:3], v[46:47] op_sel_hi:[1,0,1]
	ds_read_b128 v[12:15], v125 offset:720
	ds_read_b128 v[28:31], v125 offset:736
	ds_read_b128 v[44:47], v125 offset:752
	v_pk_fma_f32 v[20:21], v[52:53], v[6:7], v[20:21] op_sel_hi:[1,0,1]
	v_pk_fma_f32 v[24:25], v[52:53], v[6:7], v[24:25] op_sel:[0,1,0]
	v_pk_fma_f32 v[36:37], v[52:53], v[10:11], v[36:37] op_sel_hi:[1,0,1]
	v_pk_fma_f32 v[40:41], v[52:53], v[10:11], v[40:41] op_sel:[0,1,0]
	v_pk_fma_f32 v[48:49], v[52:53], v[2:3], v[48:49] op_sel_hi:[1,0,1]
	s_waitcnt vmcnt(0) lgkmcnt(2)
	v_pk_fma_f32 v[4:5], v[82:83], v[12:13], v[54:55] op_sel_hi:[1,0,1]
	v_pk_fma_f32 v[2:3], v[80:81], v[12:13], v[56:57] op_sel_hi:[1,0,1]
	v_pk_fma_f32 v[8:9], v[82:83], v[12:13], v[58:59] op_sel:[0,1,0]
	v_pk_fma_f32 v[6:7], v[80:81], v[12:13], v[60:61] op_sel:[0,1,0]
	v_pk_fma_f32 v[12:13], v[82:83], v[14:15], v[62:63] op_sel_hi:[1,0,1]
	v_pk_fma_f32 v[10:11], v[80:81], v[14:15], v[64:65] op_sel_hi:[1,0,1]
	v_mov_b32_e32 v14, v15
	s_waitcnt lgkmcnt(1)
	v_pk_fma_f32 v[20:21], v[82:83], v[28:29], v[20:21] op_sel_hi:[1,0,1]
	v_pk_fma_f32 v[18:19], v[80:81], v[28:29], v[18:19] op_sel_hi:[1,0,1]
	v_pk_fma_f32 v[24:25], v[82:83], v[28:29], v[24:25] op_sel:[0,1,0]
	v_pk_fma_f32 v[22:23], v[80:81], v[28:29], v[22:23] op_sel:[0,1,0]
	v_pk_fma_f32 v[28:29], v[82:83], v[30:31], v[70:71] op_sel_hi:[1,0,1]
	v_pk_fma_f32 v[26:27], v[80:81], v[30:31], v[26:27] op_sel_hi:[1,0,1]
	v_mov_b32_e32 v30, v31
	s_waitcnt lgkmcnt(0)
	v_pk_fma_f32 v[36:37], v[82:83], v[44:45], v[36:37] op_sel_hi:[1,0,1]
	v_pk_fma_f32 v[34:35], v[80:81], v[44:45], v[34:35] op_sel_hi:[1,0,1]
	v_pk_fma_f32 v[40:41], v[82:83], v[44:45], v[40:41] op_sel:[0,1,0]
	v_pk_fma_f32 v[38:39], v[80:81], v[44:45], v[38:39] op_sel:[0,1,0]
	v_pk_fma_f32 v[44:45], v[82:83], v[46:47], v[74:75] op_sel_hi:[1,0,1]
	v_pk_fma_f32 v[42:43], v[80:81], v[46:47], v[42:43] op_sel_hi:[1,0,1]
	v_mov_b32_e32 v46, v47
	v_pk_fma_f32 v[16:17], v[82:83], v[14:15], v[16:17] op_sel_hi:[1,0,1]
	v_pk_fma_f32 v[14:15], v[80:81], v[14:15], v[68:69] op_sel_hi:[1,0,1]
	v_pk_fma_f32 v[32:33], v[82:83], v[30:31], v[32:33] op_sel_hi:[1,0,1]
	v_pk_fma_f32 v[30:31], v[80:81], v[30:31], v[72:73] op_sel_hi:[1,0,1]
	v_pk_fma_f32 v[48:49], v[82:83], v[46:47], v[48:49] op_sel_hi:[1,0,1]
	v_pk_fma_f32 v[46:47], v[80:81], v[46:47], v[50:51] op_sel_hi:[1,0,1]
	s_cbranch_scc0 .LBB0_1233
	s_barrier
	ds_write_b128 v66, v[2:5]
	ds_write_b128 v66, v[6:9] offset:1024
	ds_write_b128 v66, v[10:13] offset:2048
	ds_write_b128 v66, v[14:17] offset:3072
	ds_write_b128 v66, v[18:21] offset:4096
	ds_write_b128 v66, v[22:25] offset:5120
	ds_write_b128 v66, v[26:29] offset:6144
	ds_write_b128 v66, v[30:33] offset:7168
	ds_write_b128 v66, v[34:37] offset:8192
	ds_write_b128 v66, v[38:41] offset:9216
	ds_write_b128 v66, v[42:45] offset:10240
	ds_write_b128 v66, v[46:49] offset:11264
	s_waitcnt lgkmcnt(0)
	s_barrier
	s_and_saveexec_b64 s[10:11], s[40:41]
	s_cbranch_execz .LBB0_1222
	v_readlane_b32 s5, v251, 26
	s_add_u32 s8, s5, s8
	v_readlane_b32 s5, v251, 27
	s_addc_u32 s9, s5, s9
	s_add_i32 s16, s20, s4
	v_lshl_add_u32 v2, v124, 2, 0
	s_mov_b64 s[4:5], 0
	v_mov_b32_e32 v3, v124

.LBB0_1295:
	s_ashr_i32 s3, s4, 31
	s_mul_hi_u32 s22, s28, s4
	s_mul_i32 s3, s28, s3
	s_add_i32 s23, s22, s3
	s_mul_i32 s22, s28, s4
	s_lshl_b64 s[22:23], s[22:23], 2
	s_add_u32 s46, s46, s22
	s_addc_u32 s47, s47, s23
	s_ashr_i32 s3, s2, 31
	s_lshl_b64 s[22:23], s[2:3], 2
	s_add_u32 s22, s46, s22
	s_waitcnt vmcnt(0)
	v_mul_lo_u32 v2, s28, v52
	s_addc_u32 s23, s47, s23
	v_or_b32_e32 v2, v2, v53
	v_mov_b32_e32 v3, v67
	v_lshl_add_u64 v[26:27], v[2:3], 2, s[22:23]
	s_lshl_b32 s22, s28, 5
	s_mov_b32 s23, s29
	v_lshl_add_u64 v[10:11], s[22:23], 2, v[26:27]
	s_mul_i32 s22, s28, 33
	v_lshl_add_u64 v[14:15], s[22:23], 2, v[26:27]
	s_lshl_b32 s22, s28, 6
	v_lshl_add_u64 v[18:19], s[22:23], 2, v[26:27]
	s_mul_i32 s22, s28, 0x41
	v_lshl_add_u64 v[6:7], s[28:29], 2, v[26:27]
	v_lshl_add_u64 v[22:23], s[22:23], 2, v[26:27]
	s_mul_i32 s22, s28, 0x60
	s_mulk_i32 s28, 0x61
	v_lshl_add_u64 v[28:29], s[22:23], 2, v[26:27]
	v_lshl_add_u64 v[30:31], s[28:29], 2, v[26:27]
	flat_load_dwordx4 v[2:5], v[26:27] nt
	s_nop 0
	flat_load_dwordx4 v[6:9], v[6:7] nt
	s_nop 0
	flat_load_dwordx4 v[10:13], v[10:11] nt
	s_nop 0
	flat_load_dwordx4 v[14:17], v[14:15] nt
	s_nop 0
	flat_load_dwordx4 v[18:21], v[18:19] nt
	s_nop 0
	flat_load_dwordx4 v[22:25], v[22:23] nt
	s_nop 0
	flat_load_dwordx4 v[26:29], v[28:29] nt
	s_nop 0
	flat_load_dwordx4 v[30:33], v[30:31] nt

.LBB0_1309:
	s_ashr_i32 s5, s47, 31
	s_mul_hi_u32 s50, s47, s28
	s_mul_i32 s5, s5, s28
	s_add_i32 s51, s50, s5
	s_mul_i32 s50, s47, s28
	s_lshl_b64 s[50:51], s[50:51], 2
	s_add_u32 s5, s48, s50
	s_addc_u32 s48, s49, s51
	s_ashr_i32 s47, s46, 31
	s_lshl_b64 s[46:47], s[46:47], 2
	s_add_u32 s46, s5, s46
	v_mul_lo_u32 v2, s28, v52
	s_addc_u32 s47, s48, s47
	v_or_b32_e32 v2, v2, v53
	v_mov_b32_e32 v3, v67
	v_lshl_add_u64 v[26:27], v[2:3], 2, s[46:47]
	s_lshl_b32 s46, s28, 5
	s_mov_b32 s47, s29
	v_lshl_add_u64 v[10:11], s[46:47], 2, v[26:27]
	s_mul_i32 s46, s28, 33
	v_lshl_add_u64 v[14:15], s[46:47], 2, v[26:27]
	s_lshl_b32 s46, s28, 6
	v_lshl_add_u64 v[18:19], s[46:47], 2, v[26:27]
	s_mul_i32 s46, s28, 0x41
	v_lshl_add_u64 v[6:7], s[28:29], 2, v[26:27]
	v_lshl_add_u64 v[22:23], s[46:47], 2, v[26:27]
	s_mul_i32 s46, s28, 0x60
	s_mulk_i32 s28, 0x61
	v_lshl_add_u64 v[28:29], s[46:47], 2, v[26:27]
	v_lshl_add_u64 v[30:31], s[28:29], 2, v[26:27]
	flat_load_dwordx4 v[2:5], v[26:27] nt
	s_nop 0
	flat_load_dwordx4 v[6:9], v[6:7] nt
	s_nop 0
	flat_load_dwordx4 v[10:13], v[10:11] nt
	s_nop 0
	flat_load_dwordx4 v[14:17], v[14:15] nt
	s_nop 0
	flat_load_dwordx4 v[18:21], v[18:19] nt
	s_nop 0
	flat_load_dwordx4 v[22:25], v[22:23] nt
	s_nop 0
	flat_load_dwordx4 v[26:29], v[28:29] nt
	s_nop 0
	flat_load_dwordx4 v[30:33], v[30:31] nt
